# K-loops: first trip peeled, every accumulator's first MFMA takes 0 as C (no per-tile zeroing of 128/64 accumulator registers)
# speedup vs baseline: 1.0061x; 1.0061x over previous
; DI int TID() { int t = (int)__builtin_amdgcn_workitem_id_x(); asm volatile("" : "+v"(t)); return t; }
; #define BLOAD(A_, B_, kt) do { _Pragma("unroll") for (int i = 0; i < 4; ++i) { \
;     A_[i] = *(const u32x4*)((const char*)Ap + (aoff + (unsigned)(32 * i * lda + (kt) * 64) * 2u)); B_[i] = *(const u32x4*)((const char*)Wt + (woff + (unsigned)(32 * i * K + (kt) * 64) * 2u)); } } while (0)
; #define BLOAD(A_, B_, kt) do { _Pragma("unroll") for (int i = 0; i < 4; ++i) { \
;     A_[i] = *(const u32x4*)((const char*)Ap + (aoff + (unsigned)(32 * i * lda + (kt) * 64) * 2u)); B_[i] = *(const u32x4*)((const char*)Wt + (woff + (unsigned)(32 * i * K + (kt) * 64) * 2u)); } } while (0)
; #define BSTORE(A_, B_, buf) do { _Pragma("unroll") for (int i = 0; i < 4; ++i) { \
;     *(u32x4*)&As[(buf) * GBUF + (srow + 32 * i) * LDT + sc8] = A_[i]; \
;     *(u32x4*)&Bs[(buf) * GBUF + (srow + 32 * i) * LDT + sc8] = B_[i]; } } while (0)
; template <int NK>
; DI void gemm_run(PF& pf, const u16* __restrict__ Ap, int lda, const u16* __restrict__ Wt, f32x16 (&acc)[2][2], char* smem) {
;     ...
;   __builtin_amdgcn_s_setprio(0);
;   __syncthreads();
;   BSTORE(pf.a0, pf.b0, 0);
;   BLOAD(pf.a0, pf.b0, 2);
;   __syncthreads();
; #pragma unroll
;   for (int kt = 0; kt < nk; kt += 2) {
;     BCOMP(0);
;     BSTORE(pf.a1, pf.b1, 1);
;     if (kt + 3 < nk) BLOAD(pf.a1, pf.b1, kt + 3);
;     __syncthreads();
;     BCOMP(1);
;     if (kt + 2 < nk) { BSTORE(pf.a0, pf.b0, 0); if (kt + 4 < nk) BLOAD(pf.a0, pf.b0, kt + 4); }
;     __syncthreads();
;   }
; DI void tile_ffn2(const Params& p, int l, const Chunk& ck, int tile, int next, PF& pf, char* smem) {
;   float* Cs = (float*)smem;
;   const int tid = TID(); const int mi = tile & (MTN - 1), ni = tile >> MTS; const int m0 = mi * 128, n0 = ni * 128;
;   f32x16 acc[2][2]; zero_acc(acc);
;   { const u16* Ap; const u16* Wt; ffn2_ptrs(p, l, tile, Ap, Wt); gemm_run<64>(pf, Ap, 4096, Wt, acc, smem); }
.LBB1_206:
	s_add_i32 s25, s26, s78
	s_cmpk_gt_i32 s25, 0x1ff
	s_cselect_b64 s[28:29], -1, 0
	s_cmpk_lt_i32 s25, 0x200
	s_cselect_b32 s0, s25, -1
	s_and_b32 s16, s41, 0x3f80000
	s_and_b32 s36, s26, 0xffffff80
	s_add_i32 s26, s26, s36
	s_lshl_b32 s36, s36, 1
	s_lshl_b32 s16, s16, 1
	s_add_u32 vcc_lo, s17, s16
	v_mov_b32_e32 v0, v172
	s_addc_u32 vcc_hi, s27, 0
	s_ashr_i32 s37, s36, 31
	s_lshl_b64 s[30:31], s[36:37], 6
	s_add_u32 s30, s34, s30
	s_addc_u32 s31, s40, s31
	s_setprio 0
	s_waitcnt lgkmcnt(0)
	s_lshr_b32 s16, s16, 7
	s_add_u32 s42, s17, s16
	s_addc_u32 s43, s27, 0
	v_and_b32_e32 v174, 63, v172
	v_lshrrev_b32_e32 v175, 6, v172
	v_bfe_u32 v176, v174, 4, 2
	v_lshrrev_b32_e32 v177, 1, v176
	v_xor_b32_e32 v176, v176, v177
	v_and_b32_e32 v176, 1, v176
	v_lshl_or_b32 v176, v176, 1, v177
	v_xor_b32_e32 v176, v176, v174
	v_and_b32_e32 v176, 3, v176
	v_lshlrev_b32_e32 v176, 4, v176
	v_lshrrev_b32_e32 v177, 2, v174
	v_lshl_add_u32 v137, v175, 5, v177
	v_lshl_add_u32 v137, v137, 6, v176
	v_mov_b32_e32 v150, v137
	v_lshl_add_u32 v151, v175, 6, v177
	v_lshl_add_u32 v151, v151, 6, v176
	v_mov_b32_e32 v152, v151
	v_mov_b32_e32 v153, v151
	v_mov_b32_e32 v154, v151
	v_readfirstlane_b32 s16, v175
	s_lshl_b32 s0, s16, 12
	s_lshl_b32 s16, s16, 11
	s_add_u32 s0, s0, 0x2000
	v_bfe_u32 v176, v174, 2, 2
	v_lshrrev_b32_e32 v177, 1, v176
	v_xor_b32_e32 v176, v176, v177
	v_and_b32_e32 v176, 1, v176
	v_lshl_or_b32 v176, v176, 1, v177
	v_lshrrev_b32_e32 v177, 4, v174
	v_xor_b32_e32 v176, v176, v177
	v_lshlrev_b32_e32 v176, 4, v176
	v_and_b32_e32 v174, 15, v174
	v_lshl_add_u32 v174, v174, 6, v176
	v_lshrrev_b32_e32 v176, 1, v175
	v_and_b32_e32 v177, 1, v175
	v_lshl_add_u32 v126, v176, 12, v174
	v_lshl_add_u32 v128, v177, 12, v174
	v_add_u32_e32 v128, 0x2000, v128
	s_barrier
	s_add_u32 m0, s16, 0x0
	s_nop 0
	global_load_lds_dwordx4 v137, s[42:43]
	global_load_lds_dwordx4 v150, s[42:43] offset:1024
	s_add_u32 m0, s0, 0x0
	s_nop 0
	global_load_lds_dwordx4 v151, s[30:31]
	global_load_lds_dwordx4 v152, s[30:31] offset:1024
	global_load_lds_dwordx4 v153, s[30:31] offset:2048
	global_load_lds_dwordx4 v154, s[30:31] offset:3072
	s_add_u32 m0, s16, 0x6000
	s_add_u32 s42, s42, 0x100000
	s_addc_u32 s43, s43, 0
	global_load_lds_dwordx4 v137, s[42:43]
	global_load_lds_dwordx4 v150, s[42:43] offset:1024
	s_add_u32 m0, s0, 0x6000
	s_add_u32 s30, s30, 0x10000
	s_addc_u32 s31, s31, 0
	global_load_lds_dwordx4 v151, s[30:31]
	global_load_lds_dwordx4 v152, s[30:31] offset:1024
	global_load_lds_dwordx4 v153, s[30:31] offset:2048
	global_load_lds_dwordx4 v154, s[30:31] offset:3072
	s_waitcnt vmcnt(6)
	s_barrier
	ds_read_b128 v[224:227], v126 offset:0
	ds_read_b128 v[240:243], v128 offset:0
	ds_read_b128 v[244:247], v128 offset:1024
	ds_read_b128 v[248:251], v128 offset:2048
	ds_read_b128 v[156:159], v128 offset:3072
	s_add_u32 m0, s16, 0xc000
	s_add_u32 s42, s42, 0x100000
	s_addc_u32 s43, s43, 0
	global_load_lds_dwordx4 v137, s[42:43]
	global_load_lds_dwordx4 v150, s[42:43] offset:1024
	s_add_u32 m0, s0, 0xc000
	s_add_u32 s30, s30, 0x10000
	s_addc_u32 s31, s31, 0
	global_load_lds_dwordx4 v151, s[30:31]
	global_load_lds_dwordx4 v152, s[30:31] offset:1024
	global_load_lds_dwordx4 v153, s[30:31] offset:2048
	global_load_lds_dwordx4 v154, s[30:31] offset:3072
	ds_read_b128 v[228:231], v126 offset:1024
	ds_read_b128 v[232:235], v126 offset:2048
	ds_read_b128 v[236:239], v126 offset:3072
	ds_read_b128 v[160:163], v128 offset:8192
	ds_read_b128 v[164:167], v128 offset:9216
	ds_read_b128 v[168:171], v128 offset:10240
	ds_read_b128 v[122:125], v128 offset:11264
	s_waitcnt lgkmcnt(10)
	v_mfma_f32_16x16x32_bf16 v[2:5], v[240:243], v[224:227], 0
	s_waitcnt lgkmcnt(9)
	v_mfma_f32_16x16x32_bf16 v[6:9], v[244:247], v[224:227], 0
	s_waitcnt lgkmcnt(8)
	v_mfma_f32_16x16x32_bf16 v[10:13], v[248:251], v[224:227], 0
	s_waitcnt lgkmcnt(7)
	v_mfma_f32_16x16x32_bf16 v[14:17], v[156:159], v[224:227], 0
	s_waitcnt lgkmcnt(6)
	v_mfma_f32_16x16x32_bf16 v[18:21], v[240:243], v[228:231], 0
	v_mfma_f32_16x16x32_bf16 v[22:25], v[244:247], v[228:231], 0
	v_mfma_f32_16x16x32_bf16 v[26:29], v[248:251], v[228:231], 0
	v_mfma_f32_16x16x32_bf16 v[30:33], v[156:159], v[228:231], 0
	s_waitcnt lgkmcnt(5)
	v_mfma_f32_16x16x32_bf16 v[34:37], v[240:243], v[232:235], 0
	v_mfma_f32_16x16x32_bf16 v[38:41], v[244:247], v[232:235], 0
	v_mfma_f32_16x16x32_bf16 v[42:45], v[248:251], v[232:235], 0
	v_mfma_f32_16x16x32_bf16 v[46:49], v[156:159], v[232:235], 0
	s_waitcnt lgkmcnt(4)
	v_mfma_f32_16x16x32_bf16 v[50:53], v[240:243], v[236:239], 0
	v_mfma_f32_16x16x32_bf16 v[54:57], v[244:247], v[236:239], 0
	v_mfma_f32_16x16x32_bf16 v[58:61], v[248:251], v[236:239], 0
	v_mfma_f32_16x16x32_bf16 v[62:65], v[156:159], v[236:239], 0
	s_waitcnt lgkmcnt(3)
	v_mfma_f32_16x16x32_bf16 v[74:77], v[160:163], v[224:227], 0
	s_waitcnt lgkmcnt(2)
	v_mfma_f32_16x16x32_bf16 v[78:81], v[164:167], v[224:227], 0
	s_waitcnt lgkmcnt(1)
	v_mfma_f32_16x16x32_bf16 v[82:85], v[168:171], v[224:227], 0
	s_waitcnt lgkmcnt(0)
	v_mfma_f32_16x16x32_bf16 v[86:89], v[122:125], v[224:227], 0
	v_mfma_f32_16x16x32_bf16 v[90:93], v[160:163], v[228:231], 0
	v_mfma_f32_16x16x32_bf16 v[94:97], v[164:167], v[228:231], 0
	v_mfma_f32_16x16x32_bf16 v[98:101], v[168:171], v[228:231], 0
	v_mfma_f32_16x16x32_bf16 v[102:105], v[122:125], v[228:231], 0
	v_mfma_f32_16x16x32_bf16 v[106:109], v[160:163], v[232:235], 0
	v_mfma_f32_16x16x32_bf16 v[110:113], v[164:167], v[232:235], 0
	v_mfma_f32_16x16x32_bf16 v[114:117], v[168:171], v[232:235], 0
	v_mfma_f32_16x16x32_bf16 v[118:121], v[122:125], v[232:235], 0
	v_mfma_f32_16x16x32_bf16 v[208:211], v[160:163], v[236:239], 0
	v_mfma_f32_16x16x32_bf16 v[212:215], v[164:167], v[236:239], 0
	v_mfma_f32_16x16x32_bf16 v[216:219], v[168:171], v[236:239], 0
	v_mfma_f32_16x16x32_bf16 v[220:223], v[122:125], v[236:239], 0
	s_waitcnt vmcnt(6)
	s_barrier
; #define BLOAD(A_, B_, kt) do { _Pragma("unroll") for (int i = 0; i < 4; ++i) { \
;     A_[i] = *(const u32x4*)((const char*)Ap + (aoff + (unsigned)(32 * i * lda + (kt) * 64) * 2u)); B_[i] = *(const u32x4*)((const char*)Wt + (woff + (unsigned)(32 * i * K + (kt) * 64) * 2u)); } } while (0)
; #define BLOAD(A_, B_, kt) do { _Pragma("unroll") for (int i = 0; i < 4; ++i) { \
;     A_[i] = *(const u32x4*)((const char*)Ap + (aoff + (unsigned)(32 * i * lda + (kt) * 64) * 2u)); B_[i] = *(const u32x4*)((const char*)Wt + (woff + (unsigned)(32 * i * K + (kt) * 64) * 2u)); } } while (0)
; #define BSTORE(A_, B_, buf) do { _Pragma("unroll") for (int i = 0; i < 4; ++i) { \
;     *(u32x4*)&As[(buf) * GBUF + (srow + 32 * i) * LDT + sc8] = A_[i]; \
;     *(u32x4*)&Bs[(buf) * GBUF + (srow + 32 * i) * LDT + sc8] = B_[i]; } } while (0)
; template <int NK>
; DI void gemm_run(PF& pf, const u16* __restrict__ Ap, int lda, const u16* __restrict__ Wt, f32x16 (&acc)[2][2], char* smem) {
;     ...
;   __builtin_amdgcn_s_setprio(0);
;   __syncthreads();
;   BSTORE(pf.a0, pf.b0, 0);
;   BLOAD(pf.a0, pf.b0, 2);
;   __syncthreads();
; #pragma unroll
;   for (int kt = 0; kt < nk; kt += 2) {
;     BCOMP(0);
;     BSTORE(pf.a1, pf.b1, 1);
;     if (kt + 3 < nk) BLOAD(pf.a1, pf.b1, kt + 3);
;     __syncthreads();
;     BCOMP(1);
;     if (kt + 2 < nk) { BSTORE(pf.a0, pf.b0, 0); if (kt + 4 < nk) BLOAD(pf.a0, pf.b0, kt + 4); }
;     __syncthreads();
;   }
	ds_read_b128 v[224:227], v126 offset:24576
	ds_read_b128 v[240:243], v128 offset:24576
	ds_read_b128 v[244:247], v128 offset:25600
	ds_read_b128 v[248:251], v128 offset:26624
	ds_read_b128 v[156:159], v128 offset:27648
	s_add_u32 m0, s16, 0x0
	s_add_u32 s42, s42, 0x100000
	s_addc_u32 s43, s43, 0
	global_load_lds_dwordx4 v137, s[42:43]
	global_load_lds_dwordx4 v150, s[42:43] offset:1024
	s_add_u32 m0, s0, 0x0
	s_add_u32 s30, s30, 0x10000
	s_addc_u32 s31, s31, 0
	global_load_lds_dwordx4 v151, s[30:31]
	global_load_lds_dwordx4 v152, s[30:31] offset:1024
	global_load_lds_dwordx4 v153, s[30:31] offset:2048
	global_load_lds_dwordx4 v154, s[30:31] offset:3072
	ds_read_b128 v[228:231], v126 offset:25600
	ds_read_b128 v[232:235], v126 offset:26624
	ds_read_b128 v[236:239], v126 offset:27648
	ds_read_b128 v[160:163], v128 offset:32768
	ds_read_b128 v[164:167], v128 offset:33792
	ds_read_b128 v[168:171], v128 offset:34816
	ds_read_b128 v[122:125], v128 offset:35840
	s_waitcnt lgkmcnt(10)
	v_mfma_f32_16x16x32_bf16 v[2:5], v[240:243], v[224:227], v[2:5]
	s_waitcnt lgkmcnt(9)
	v_mfma_f32_16x16x32_bf16 v[6:9], v[244:247], v[224:227], v[6:9]
	s_waitcnt lgkmcnt(8)
	v_mfma_f32_16x16x32_bf16 v[10:13], v[248:251], v[224:227], v[10:13]
	s_waitcnt lgkmcnt(7)
	v_mfma_f32_16x16x32_bf16 v[14:17], v[156:159], v[224:227], v[14:17]
	s_waitcnt lgkmcnt(6)
	v_mfma_f32_16x16x32_bf16 v[18:21], v[240:243], v[228:231], v[18:21]
	v_mfma_f32_16x16x32_bf16 v[22:25], v[244:247], v[228:231], v[22:25]
	v_mfma_f32_16x16x32_bf16 v[26:29], v[248:251], v[228:231], v[26:29]
	v_mfma_f32_16x16x32_bf16 v[30:33], v[156:159], v[228:231], v[30:33]
	s_waitcnt lgkmcnt(5)
	v_mfma_f32_16x16x32_bf16 v[34:37], v[240:243], v[232:235], v[34:37]
	v_mfma_f32_16x16x32_bf16 v[38:41], v[244:247], v[232:235], v[38:41]
	v_mfma_f32_16x16x32_bf16 v[42:45], v[248:251], v[232:235], v[42:45]
	v_mfma_f32_16x16x32_bf16 v[46:49], v[156:159], v[232:235], v[46:49]
	s_waitcnt lgkmcnt(4)
	v_mfma_f32_16x16x32_bf16 v[50:53], v[240:243], v[236:239], v[50:53]
	v_mfma_f32_16x16x32_bf16 v[54:57], v[244:247], v[236:239], v[54:57]
	v_mfma_f32_16x16x32_bf16 v[58:61], v[248:251], v[236:239], v[58:61]
	v_mfma_f32_16x16x32_bf16 v[62:65], v[156:159], v[236:239], v[62:65]
	s_waitcnt lgkmcnt(3)
	v_mfma_f32_16x16x32_bf16 v[74:77], v[160:163], v[224:227], v[74:77]
	s_waitcnt lgkmcnt(2)
	v_mfma_f32_16x16x32_bf16 v[78:81], v[164:167], v[224:227], v[78:81]
	s_waitcnt lgkmcnt(1)
	v_mfma_f32_16x16x32_bf16 v[82:85], v[168:171], v[224:227], v[82:85]
	s_waitcnt lgkmcnt(0)
	v_mfma_f32_16x16x32_bf16 v[86:89], v[122:125], v[224:227], v[86:89]
	v_mfma_f32_16x16x32_bf16 v[90:93], v[160:163], v[228:231], v[90:93]
	v_mfma_f32_16x16x32_bf16 v[94:97], v[164:167], v[228:231], v[94:97]
	v_mfma_f32_16x16x32_bf16 v[98:101], v[168:171], v[228:231], v[98:101]
	v_mfma_f32_16x16x32_bf16 v[102:105], v[122:125], v[228:231], v[102:105]
	v_mfma_f32_16x16x32_bf16 v[106:109], v[160:163], v[232:235], v[106:109]
	v_mfma_f32_16x16x32_bf16 v[110:113], v[164:167], v[232:235], v[110:113]
	v_mfma_f32_16x16x32_bf16 v[114:117], v[168:171], v[232:235], v[114:117]
	v_mfma_f32_16x16x32_bf16 v[118:121], v[122:125], v[232:235], v[118:121]
	v_mfma_f32_16x16x32_bf16 v[208:211], v[160:163], v[236:239], v[208:211]
	v_mfma_f32_16x16x32_bf16 v[212:215], v[164:167], v[236:239], v[212:215]
	v_mfma_f32_16x16x32_bf16 v[216:219], v[168:171], v[236:239], v[216:219]
	v_mfma_f32_16x16x32_bf16 v[220:223], v[122:125], v[236:239], v[220:223]
	s_waitcnt vmcnt(6)
	s_barrier
	ds_read_b128 v[224:227], v126 offset:49152
	ds_read_b128 v[240:243], v128 offset:49152
	ds_read_b128 v[244:247], v128 offset:50176
	ds_read_b128 v[248:251], v128 offset:51200
	ds_read_b128 v[156:159], v128 offset:52224
	s_add_u32 m0, s16, 0x6000
	s_add_u32 s42, s42, 0x100000
	s_addc_u32 s43, s43, 0
	global_load_lds_dwordx4 v137, s[42:43]
	global_load_lds_dwordx4 v150, s[42:43] offset:1024
	s_add_u32 m0, s0, 0x6000
	s_add_u32 s30, s30, 0x10000
	s_addc_u32 s31, s31, 0
	global_load_lds_dwordx4 v151, s[30:31]
	global_load_lds_dwordx4 v152, s[30:31] offset:1024
	global_load_lds_dwordx4 v153, s[30:31] offset:2048
	global_load_lds_dwordx4 v154, s[30:31] offset:3072
	ds_read_b128 v[228:231], v126 offset:50176
	ds_read_b128 v[232:235], v126 offset:51200
	ds_read_b128 v[236:239], v126 offset:52224
	ds_read_b128 v[160:163], v128 offset:57344
	ds_read_b128 v[164:167], v128 offset:58368
	ds_read_b128 v[168:171], v128 offset:59392
	ds_read_b128 v[122:125], v128 offset:60416
	s_waitcnt lgkmcnt(10)
	v_mfma_f32_16x16x32_bf16 v[2:5], v[240:243], v[224:227], v[2:5]
	s_waitcnt lgkmcnt(9)
	v_mfma_f32_16x16x32_bf16 v[6:9], v[244:247], v[224:227], v[6:9]
	s_waitcnt lgkmcnt(8)
	v_mfma_f32_16x16x32_bf16 v[10:13], v[248:251], v[224:227], v[10:13]
	s_waitcnt lgkmcnt(7)
	v_mfma_f32_16x16x32_bf16 v[14:17], v[156:159], v[224:227], v[14:17]
	s_waitcnt lgkmcnt(6)
	v_mfma_f32_16x16x32_bf16 v[18:21], v[240:243], v[228:231], v[18:21]
	v_mfma_f32_16x16x32_bf16 v[22:25], v[244:247], v[228:231], v[22:25]
	v_mfma_f32_16x16x32_bf16 v[26:29], v[248:251], v[228:231], v[26:29]
	v_mfma_f32_16x16x32_bf16 v[30:33], v[156:159], v[228:231], v[30:33]
	s_waitcnt lgkmcnt(5)
	v_mfma_f32_16x16x32_bf16 v[34:37], v[240:243], v[232:235], v[34:37]
	v_mfma_f32_16x16x32_bf16 v[38:41], v[244:247], v[232:235], v[38:41]
	v_mfma_f32_16x16x32_bf16 v[42:45], v[248:251], v[232:235], v[42:45]
	v_mfma_f32_16x16x32_bf16 v[46:49], v[156:159], v[232:235], v[46:49]
	s_waitcnt lgkmcnt(4)
	v_mfma_f32_16x16x32_bf16 v[50:53], v[240:243], v[236:239], v[50:53]
	v_mfma_f32_16x16x32_bf16 v[54:57], v[244:247], v[236:239], v[54:57]
	v_mfma_f32_16x16x32_bf16 v[58:61], v[248:251], v[236:239], v[58:61]
	v_mfma_f32_16x16x32_bf16 v[62:65], v[156:159], v[236:239], v[62:65]
	s_waitcnt lgkmcnt(3)
	v_mfma_f32_16x16x32_bf16 v[74:77], v[160:163], v[224:227], v[74:77]
	s_waitcnt lgkmcnt(2)
	v_mfma_f32_16x16x32_bf16 v[78:81], v[164:167], v[224:227], v[78:81]
	s_waitcnt lgkmcnt(1)
	v_mfma_f32_16x16x32_bf16 v[82:85], v[168:171], v[224:227], v[82:85]
	s_waitcnt lgkmcnt(0)
	v_mfma_f32_16x16x32_bf16 v[86:89], v[122:125], v[224:227], v[86:89]
	v_mfma_f32_16x16x32_bf16 v[90:93], v[160:163], v[228:231], v[90:93]
	v_mfma_f32_16x16x32_bf16 v[94:97], v[164:167], v[228:231], v[94:97]
	v_mfma_f32_16x16x32_bf16 v[98:101], v[168:171], v[228:231], v[98:101]
	v_mfma_f32_16x16x32_bf16 v[102:105], v[122:125], v[228:231], v[102:105]
	v_mfma_f32_16x16x32_bf16 v[106:109], v[160:163], v[232:235], v[106:109]
	v_mfma_f32_16x16x32_bf16 v[110:113], v[164:167], v[232:235], v[110:113]
	v_mfma_f32_16x16x32_bf16 v[114:117], v[168:171], v[232:235], v[114:117]
	v_mfma_f32_16x16x32_bf16 v[118:121], v[122:125], v[232:235], v[118:121]
	v_mfma_f32_16x16x32_bf16 v[208:211], v[160:163], v[236:239], v[208:211]
	v_mfma_f32_16x16x32_bf16 v[212:215], v[164:167], v[236:239], v[212:215]
	v_mfma_f32_16x16x32_bf16 v[216:219], v[168:171], v[236:239], v[216:219]
	v_mfma_f32_16x16x32_bf16 v[220:223], v[122:125], v[236:239], v[220:223]
	s_mov_b32 s46, 41

; DI int TID() { int t = (int)__builtin_amdgcn_workitem_id_x(); asm volatile("" : "+v"(t)); return t; }
; #define BLOAD(A_, B_, kt) do { _Pragma("unroll") for (int i = 0; i < 4; ++i) { \
;     A_[i] = *(const u32x4*)((const char*)Ap + (aoff + (unsigned)(32 * i * lda + (kt) * 64) * 2u)); B_[i] = *(const u32x4*)((const char*)Wt + (woff + (unsigned)(32 * i * K + (kt) * 64) * 2u)); } } while (0)
; DI RowSS rowss_load(const float* ps, int m0) { const int tid = TID(); const float* q = ps + (size_t)(m0 + (tid >> 1)) * 16 + (tid & 1) * 8; RowSS r; r.a = *(const f32x4*)q; r.b = *(const f32x4*)(q + 4); return r; }
; #define BLOAD(A_, B_, kt) do { _Pragma("unroll") for (int i = 0; i < 4; ++i) { \
;     A_[i] = *(const u32x4*)((const char*)Ap + (aoff + (unsigned)(32 * i * lda + (kt) * 64) * 2u)); B_[i] = *(const u32x4*)((const char*)Wt + (woff + (unsigned)(32 * i * K + (kt) * 64) * 2u)); } } while (0)
; template <int NK>
; DI void gemm_run(PF& pf, const u16* __restrict__ Ap, int lda, const u16* __restrict__ Wt, f32x16 (&acc)[2][2], char* smem) {
;     ...
;   __builtin_amdgcn_s_setprio(0);
;   __syncthreads();
;   BSTORE(pf.a0, pf.b0, 0);
;   BLOAD(pf.a0, pf.b0, 2);
;   __syncthreads();
; #pragma unroll
;   for (int kt = 0; kt < nk; kt += 2) {
;     BCOMP(0);
;     BSTORE(pf.a1, pf.b1, 1);
;     if (kt + 3 < nk) BLOAD(pf.a1, pf.b1, kt + 3);
;     __syncthreads();
;     BCOMP(1);
;     if (kt + 2 < nk) { BSTORE(pf.a0, pf.b0, 0); if (kt + 4 < nk) BLOAD(pf.a0, pf.b0, kt + 4); }
;     __syncthreads();
;   }
; DI void tile_ffn1(const Params& p, int l, const Chunk& ck, int tile, int next, PF& pf, char* smem) {
;   float* Cs = (float*)smem; float* rinv_s = (float*)(smem + SMEM_CS);
;   const int tid = TID(); const int mi = tile & (MTN - 1), ni = tile >> MTS; const int m0 = mi * 128, n0 = ni * 128;
;   f32x16 acc[2][2]; zero_acc(acc);
;   const RowSS rss = rowss_load((const float*)(p.ws + OFF_PSMID), m0);
;   { const u16* Ap; const u16* Wt; ffn1_ptrs(p, l, tile, Ap, Wt); gemm_run<16>(pf, Ap, 1024, Wt, acc, smem); }
;   if (next >= 0) { const u16* An; const u16* Wn; ffn1_ptrs(p, l, next, An, Wn); gemm_issue(pf, An, 1024, Wn, 1024); }
;   rowss_finish(rss, rinv_s);
.LBB1_246:
	s_mov_b32 s26, s16
	s_add_i32 s16, s16, s78
	s_cmpk_gt_i32 s16, 0x7ff
	s_cselect_b64 s[24:25], -1, 0
	s_cmpk_lt_i32 s16, 0x800
	v_mov_b32_e32 v148, v172
	v_mov_b32_e32 v0, v172
	s_cselect_b32 s0, s16, -1
	s_and_b32 s41, s40, 0x3f80
	s_and_b32 s27, s35, 0xfe0000
	v_ashrrev_i32_e32 v2, 1, v0
	v_add_u32_e32 v2, s41, v2
	v_ashrrev_i32_e32 v3, 31, v2
	v_lshlrev_b64 v[2:3], 6, v[2:3]
	v_lshlrev_b32_e32 v0, 5, v0
	v_lshl_add_u64 v[2:3], s[20:21], 0, v[2:3]
	v_and_b32_e32 v0, 32, v0
	v_lshl_add_u64 v[2:3], v[2:3], 0, v[0:1]
	global_load_dwordx4 v[66:69], v[2:3], off offset:16
	global_load_dwordx4 v[70:73], v[2:3], off
	s_and_b32 s26, s26, 0xffffff80
	s_lshl_b32 s26, s26, 1
	s_lshr_b32 s27, s27, 4
	s_add_u32 s28, s17, s27
	s_addc_u32 s29, s34, 0
	s_ashr_i32 s27, s26, 31
	s_lshl_b64 s[30:31], s[26:27], 6
	s_add_u32 s30, s36, s30
	s_addc_u32 s31, s37, s31
	s_setprio 0
	s_waitcnt lgkmcnt(0)
	s_mov_b32 s0, 0
	v_and_b32_e32 v149, 63, v172
	v_lshrrev_b32_e32 v151, 6, v172
	v_bfe_u32 v152, v149, 4, 2
	v_lshrrev_b32_e32 v153, 1, v152
	v_xor_b32_e32 v152, v152, v153
	v_and_b32_e32 v152, 1, v152
	v_lshl_or_b32 v152, v152, 1, v153
	v_xor_b32_e32 v152, v152, v149
	v_and_b32_e32 v152, 3, v152
	v_lshlrev_b32_e32 v152, 4, v152
	v_lshrrev_b32_e32 v153, 2, v149
	v_lshl_add_u32 v142, v151, 5, v153
	v_lshl_add_u32 v142, v142, 6, v152
	v_mov_b32_e32 v143, v142
	v_lshl_add_u32 v144, v151, 6, v153
	v_lshl_add_u32 v144, v144, 6, v152
	v_mov_b32_e32 v145, v144
	v_mov_b32_e32 v146, v144
	v_mov_b32_e32 v147, v144
	v_readfirstlane_b32 s42, v151
	s_lshl_b32 s43, s42, 12
	s_lshl_b32 s42, s42, 11
	s_add_u32 s43, s43, 0x2000
	v_bfe_u32 v152, v149, 2, 2
	v_lshrrev_b32_e32 v153, 1, v152
	v_xor_b32_e32 v152, v152, v153
	v_and_b32_e32 v152, 1, v152
	v_lshl_or_b32 v152, v152, 1, v153
	v_lshrrev_b32_e32 v153, 4, v149
	v_xor_b32_e32 v152, v152, v153
	v_lshlrev_b32_e32 v152, 4, v152
	v_and_b32_e32 v149, 15, v149
	v_lshl_add_u32 v149, v149, 6, v152
	v_lshrrev_b32_e32 v152, 1, v151
	v_and_b32_e32 v153, 1, v151
	v_lshl_add_u32 v138, v152, 12, v149
	v_lshl_add_u32 v140, v153, 12, v149
	v_add_u32_e32 v140, 0x2000, v140
	s_barrier
	s_add_u32 m0, s42, 0x0
	s_nop 0
	global_load_lds_dwordx4 v142, s[28:29]
	global_load_lds_dwordx4 v143, s[28:29] offset:1024
	s_add_u32 m0, s43, 0x0
	s_nop 0
	global_load_lds_dwordx4 v144, s[30:31]
	global_load_lds_dwordx4 v145, s[30:31] offset:1024
	global_load_lds_dwordx4 v146, s[30:31] offset:2048
	global_load_lds_dwordx4 v147, s[30:31] offset:3072
	s_add_u32 m0, s42, 0x6000
	s_add_u32 s28, s28, 0x100000
	s_addc_u32 s29, s29, 0
	global_load_lds_dwordx4 v142, s[28:29]
	global_load_lds_dwordx4 v143, s[28:29] offset:1024
	s_add_u32 m0, s43, 0x6000
	s_add_u32 s30, s30, 0x40000
	s_addc_u32 s31, s31, 0
	global_load_lds_dwordx4 v144, s[30:31]
	global_load_lds_dwordx4 v145, s[30:31] offset:1024
	global_load_lds_dwordx4 v146, s[30:31] offset:2048
	global_load_lds_dwordx4 v147, s[30:31] offset:3072
	s_waitcnt vmcnt(6)
	s_barrier
	ds_read_b128 v[208:211], v138 offset:0
	ds_read_b128 v[224:227], v140 offset:0
	ds_read_b128 v[228:231], v140 offset:1024
	ds_read_b128 v[232:235], v140 offset:2048
	ds_read_b128 v[236:239], v140 offset:3072
	s_add_u32 m0, s42, 0xc000
	s_add_u32 s28, s28, 0x100000
	s_addc_u32 s29, s29, 0
	global_load_lds_dwordx4 v142, s[28:29]
	global_load_lds_dwordx4 v143, s[28:29] offset:1024
	s_add_u32 m0, s43, 0xc000
	s_add_u32 s30, s30, 0x40000
	s_addc_u32 s31, s31, 0
	global_load_lds_dwordx4 v144, s[30:31]
	global_load_lds_dwordx4 v145, s[30:31] offset:1024
	global_load_lds_dwordx4 v146, s[30:31] offset:2048
	global_load_lds_dwordx4 v147, s[30:31] offset:3072
	ds_read_b128 v[212:215], v138 offset:1024
	ds_read_b128 v[216:219], v138 offset:2048
	ds_read_b128 v[220:223], v138 offset:3072
	ds_read_b128 v[240:243], v140 offset:8192
	ds_read_b128 v[244:247], v140 offset:9216
	ds_read_b128 v[248:251], v140 offset:10240
	ds_read_b128 v[156:159], v140 offset:11264
	s_waitcnt lgkmcnt(10)
	v_mfma_f32_16x16x32_bf16 v[2:5], v[224:227], v[208:211], 0
	s_waitcnt lgkmcnt(9)
	v_mfma_f32_16x16x32_bf16 v[6:9], v[228:231], v[208:211], 0
	s_waitcnt lgkmcnt(8)
	v_mfma_f32_16x16x32_bf16 v[10:13], v[232:235], v[208:211], 0
	s_waitcnt lgkmcnt(7)
	v_mfma_f32_16x16x32_bf16 v[14:17], v[236:239], v[208:211], 0
	s_waitcnt lgkmcnt(6)
	v_mfma_f32_16x16x32_bf16 v[18:21], v[224:227], v[212:215], 0
	v_mfma_f32_16x16x32_bf16 v[22:25], v[228:231], v[212:215], 0
	v_mfma_f32_16x16x32_bf16 v[26:29], v[232:235], v[212:215], 0
	v_mfma_f32_16x16x32_bf16 v[30:33], v[236:239], v[212:215], 0
	s_waitcnt lgkmcnt(5)
	v_mfma_f32_16x16x32_bf16 v[34:37], v[224:227], v[216:219], 0
	v_mfma_f32_16x16x32_bf16 v[38:41], v[228:231], v[216:219], 0
	v_mfma_f32_16x16x32_bf16 v[42:45], v[232:235], v[216:219], 0
	v_mfma_f32_16x16x32_bf16 v[46:49], v[236:239], v[216:219], 0
	s_waitcnt lgkmcnt(4)
	v_mfma_f32_16x16x32_bf16 v[50:53], v[224:227], v[220:223], 0
	v_mfma_f32_16x16x32_bf16 v[54:57], v[228:231], v[220:223], 0
	v_mfma_f32_16x16x32_bf16 v[58:61], v[232:235], v[220:223], 0
	v_mfma_f32_16x16x32_bf16 v[62:65], v[236:239], v[220:223], 0
	s_waitcnt lgkmcnt(3)
	v_mfma_f32_16x16x32_bf16 v[74:77], v[240:243], v[208:211], 0
	s_waitcnt lgkmcnt(2)
	v_mfma_f32_16x16x32_bf16 v[78:81], v[244:247], v[208:211], 0
	s_waitcnt lgkmcnt(1)
	v_mfma_f32_16x16x32_bf16 v[82:85], v[248:251], v[208:211], 0
	s_waitcnt lgkmcnt(0)
	v_mfma_f32_16x16x32_bf16 v[86:89], v[156:159], v[208:211], 0
	v_mfma_f32_16x16x32_bf16 v[90:93], v[240:243], v[212:215], 0
	v_mfma_f32_16x16x32_bf16 v[94:97], v[244:247], v[212:215], 0
	v_mfma_f32_16x16x32_bf16 v[98:101], v[248:251], v[212:215], 0
	v_mfma_f32_16x16x32_bf16 v[102:105], v[156:159], v[212:215], 0
	v_mfma_f32_16x16x32_bf16 v[106:109], v[240:243], v[216:219], 0
	v_mfma_f32_16x16x32_bf16 v[110:113], v[244:247], v[216:219], 0
	v_mfma_f32_16x16x32_bf16 v[114:117], v[248:251], v[216:219], 0
	v_mfma_f32_16x16x32_bf16 v[118:121], v[156:159], v[216:219], 0
	v_mfma_f32_16x16x32_bf16 v[122:125], v[240:243], v[220:223], 0
	v_mfma_f32_16x16x32_bf16 v[126:129], v[244:247], v[220:223], 0
	v_mfma_f32_16x16x32_bf16 v[130:133], v[248:251], v[220:223], 0
	v_mfma_f32_16x16x32_bf16 v[134:137], v[156:159], v[220:223], 0
	s_waitcnt vmcnt(6)
	s_barrier
; #define BLOAD(A_, B_, kt) do { _Pragma("unroll") for (int i = 0; i < 4; ++i) { \
;     A_[i] = *(const u32x4*)((const char*)Ap + (aoff + (unsigned)(32 * i * lda + (kt) * 64) * 2u)); B_[i] = *(const u32x4*)((const char*)Wt + (woff + (unsigned)(32 * i * K + (kt) * 64) * 2u)); } } while (0)
; #define BLOAD(A_, B_, kt) do { _Pragma("unroll") for (int i = 0; i < 4; ++i) { \
;     A_[i] = *(const u32x4*)((const char*)Ap + (aoff + (unsigned)(32 * i * lda + (kt) * 64) * 2u)); B_[i] = *(const u32x4*)((const char*)Wt + (woff + (unsigned)(32 * i * K + (kt) * 64) * 2u)); } } while (0)
; #define BSTORE(A_, B_, buf) do { _Pragma("unroll") for (int i = 0; i < 4; ++i) { \
;     *(u32x4*)&As[(buf) * GBUF + (srow + 32 * i) * LDT + sc8] = A_[i]; \
;     *(u32x4*)&Bs[(buf) * GBUF + (srow + 32 * i) * LDT + sc8] = B_[i]; } } while (0)
; template <int NK>
; DI void gemm_run(PF& pf, const u16* __restrict__ Ap, int lda, const u16* __restrict__ Wt, f32x16 (&acc)[2][2], char* smem) {
;     ...
;   __builtin_amdgcn_s_setprio(0);
;   __syncthreads();
;   BSTORE(pf.a0, pf.b0, 0);
;   BLOAD(pf.a0, pf.b0, 2);
;   __syncthreads();
; #pragma unroll
;   for (int kt = 0; kt < nk; kt += 2) {
;     BCOMP(0);
;     BSTORE(pf.a1, pf.b1, 1);
;     if (kt + 3 < nk) BLOAD(pf.a1, pf.b1, kt + 3);
;     __syncthreads();
;     BCOMP(1);
;     if (kt + 2 < nk) { BSTORE(pf.a0, pf.b0, 0); if (kt + 4 < nk) BLOAD(pf.a0, pf.b0, kt + 4); }
;     __syncthreads();
;   }
	ds_read_b128 v[208:211], v138 offset:24576
	ds_read_b128 v[224:227], v140 offset:24576
	ds_read_b128 v[228:231], v140 offset:25600
	ds_read_b128 v[232:235], v140 offset:26624
	ds_read_b128 v[236:239], v140 offset:27648
	s_add_u32 m0, s42, 0x0
	s_add_u32 s28, s28, 0x100000
	s_addc_u32 s29, s29, 0
	global_load_lds_dwordx4 v142, s[28:29]
	global_load_lds_dwordx4 v143, s[28:29] offset:1024
	s_add_u32 m0, s43, 0x0
	s_add_u32 s30, s30, 0x40000
	s_addc_u32 s31, s31, 0
	global_load_lds_dwordx4 v144, s[30:31]
	global_load_lds_dwordx4 v145, s[30:31] offset:1024
	global_load_lds_dwordx4 v146, s[30:31] offset:2048
	global_load_lds_dwordx4 v147, s[30:31] offset:3072
	ds_read_b128 v[212:215], v138 offset:25600
	ds_read_b128 v[216:219], v138 offset:26624
	ds_read_b128 v[220:223], v138 offset:27648
	ds_read_b128 v[240:243], v140 offset:32768
	ds_read_b128 v[244:247], v140 offset:33792
	ds_read_b128 v[248:251], v140 offset:34816
	ds_read_b128 v[156:159], v140 offset:35840
	s_waitcnt lgkmcnt(10)
	v_mfma_f32_16x16x32_bf16 v[2:5], v[224:227], v[208:211], v[2:5]
	s_waitcnt lgkmcnt(9)
	v_mfma_f32_16x16x32_bf16 v[6:9], v[228:231], v[208:211], v[6:9]
	s_waitcnt lgkmcnt(8)
	v_mfma_f32_16x16x32_bf16 v[10:13], v[232:235], v[208:211], v[10:13]
	s_waitcnt lgkmcnt(7)
	v_mfma_f32_16x16x32_bf16 v[14:17], v[236:239], v[208:211], v[14:17]
	s_waitcnt lgkmcnt(6)
	v_mfma_f32_16x16x32_bf16 v[18:21], v[224:227], v[212:215], v[18:21]
	v_mfma_f32_16x16x32_bf16 v[22:25], v[228:231], v[212:215], v[22:25]
	v_mfma_f32_16x16x32_bf16 v[26:29], v[232:235], v[212:215], v[26:29]
	v_mfma_f32_16x16x32_bf16 v[30:33], v[236:239], v[212:215], v[30:33]
	s_waitcnt lgkmcnt(5)
	v_mfma_f32_16x16x32_bf16 v[34:37], v[224:227], v[216:219], v[34:37]
	v_mfma_f32_16x16x32_bf16 v[38:41], v[228:231], v[216:219], v[38:41]
	v_mfma_f32_16x16x32_bf16 v[42:45], v[232:235], v[216:219], v[42:45]
	v_mfma_f32_16x16x32_bf16 v[46:49], v[236:239], v[216:219], v[46:49]
	s_waitcnt lgkmcnt(4)
	v_mfma_f32_16x16x32_bf16 v[50:53], v[224:227], v[220:223], v[50:53]
	v_mfma_f32_16x16x32_bf16 v[54:57], v[228:231], v[220:223], v[54:57]
	v_mfma_f32_16x16x32_bf16 v[58:61], v[232:235], v[220:223], v[58:61]
	v_mfma_f32_16x16x32_bf16 v[62:65], v[236:239], v[220:223], v[62:65]
	s_waitcnt lgkmcnt(3)
	v_mfma_f32_16x16x32_bf16 v[74:77], v[240:243], v[208:211], v[74:77]
	s_waitcnt lgkmcnt(2)
	v_mfma_f32_16x16x32_bf16 v[78:81], v[244:247], v[208:211], v[78:81]
	s_waitcnt lgkmcnt(1)
	v_mfma_f32_16x16x32_bf16 v[82:85], v[248:251], v[208:211], v[82:85]
	s_waitcnt lgkmcnt(0)
	v_mfma_f32_16x16x32_bf16 v[86:89], v[156:159], v[208:211], v[86:89]
	v_mfma_f32_16x16x32_bf16 v[90:93], v[240:243], v[212:215], v[90:93]
	v_mfma_f32_16x16x32_bf16 v[94:97], v[244:247], v[212:215], v[94:97]
	v_mfma_f32_16x16x32_bf16 v[98:101], v[248:251], v[212:215], v[98:101]
	v_mfma_f32_16x16x32_bf16 v[102:105], v[156:159], v[212:215], v[102:105]
	v_mfma_f32_16x16x32_bf16 v[106:109], v[240:243], v[216:219], v[106:109]
	v_mfma_f32_16x16x32_bf16 v[110:113], v[244:247], v[216:219], v[110:113]
	v_mfma_f32_16x16x32_bf16 v[114:117], v[248:251], v[216:219], v[114:117]
	v_mfma_f32_16x16x32_bf16 v[118:121], v[156:159], v[216:219], v[118:121]
	v_mfma_f32_16x16x32_bf16 v[122:125], v[240:243], v[220:223], v[122:125]
	v_mfma_f32_16x16x32_bf16 v[126:129], v[244:247], v[220:223], v[126:129]
	v_mfma_f32_16x16x32_bf16 v[130:133], v[248:251], v[220:223], v[130:133]
	v_mfma_f32_16x16x32_bf16 v[134:137], v[156:159], v[220:223], v[134:137]
	s_waitcnt vmcnt(6)
	s_barrier
	ds_read_b128 v[208:211], v138 offset:49152
	ds_read_b128 v[224:227], v140 offset:49152
	ds_read_b128 v[228:231], v140 offset:50176
	ds_read_b128 v[232:235], v140 offset:51200
	ds_read_b128 v[236:239], v140 offset:52224
	s_add_u32 m0, s42, 0x6000
	s_add_u32 s28, s28, 0x100000
	s_addc_u32 s29, s29, 0
	global_load_lds_dwordx4 v142, s[28:29]
	global_load_lds_dwordx4 v143, s[28:29] offset:1024
	s_add_u32 m0, s43, 0x6000
	s_add_u32 s30, s30, 0x40000
	s_addc_u32 s31, s31, 0
	global_load_lds_dwordx4 v144, s[30:31]
	global_load_lds_dwordx4 v145, s[30:31] offset:1024
	global_load_lds_dwordx4 v146, s[30:31] offset:2048
	global_load_lds_dwordx4 v147, s[30:31] offset:3072
	ds_read_b128 v[212:215], v138 offset:50176
	ds_read_b128 v[216:219], v138 offset:51200
	ds_read_b128 v[220:223], v138 offset:52224
	ds_read_b128 v[240:243], v140 offset:57344
	ds_read_b128 v[244:247], v140 offset:58368
	ds_read_b128 v[248:251], v140 offset:59392
	ds_read_b128 v[156:159], v140 offset:60416
	s_waitcnt lgkmcnt(10)
	v_mfma_f32_16x16x32_bf16 v[2:5], v[224:227], v[208:211], v[2:5]
	s_waitcnt lgkmcnt(9)
	v_mfma_f32_16x16x32_bf16 v[6:9], v[228:231], v[208:211], v[6:9]
	s_waitcnt lgkmcnt(8)
	v_mfma_f32_16x16x32_bf16 v[10:13], v[232:235], v[208:211], v[10:13]
	s_waitcnt lgkmcnt(7)
	v_mfma_f32_16x16x32_bf16 v[14:17], v[236:239], v[208:211], v[14:17]
	s_waitcnt lgkmcnt(6)
	v_mfma_f32_16x16x32_bf16 v[18:21], v[224:227], v[212:215], v[18:21]
	v_mfma_f32_16x16x32_bf16 v[22:25], v[228:231], v[212:215], v[22:25]
	v_mfma_f32_16x16x32_bf16 v[26:29], v[232:235], v[212:215], v[26:29]
	v_mfma_f32_16x16x32_bf16 v[30:33], v[236:239], v[212:215], v[30:33]
	s_waitcnt lgkmcnt(5)
	v_mfma_f32_16x16x32_bf16 v[34:37], v[224:227], v[216:219], v[34:37]
	v_mfma_f32_16x16x32_bf16 v[38:41], v[228:231], v[216:219], v[38:41]
	v_mfma_f32_16x16x32_bf16 v[42:45], v[232:235], v[216:219], v[42:45]
	v_mfma_f32_16x16x32_bf16 v[46:49], v[236:239], v[216:219], v[46:49]
	s_waitcnt lgkmcnt(4)
	v_mfma_f32_16x16x32_bf16 v[50:53], v[224:227], v[220:223], v[50:53]
	v_mfma_f32_16x16x32_bf16 v[54:57], v[228:231], v[220:223], v[54:57]
	v_mfma_f32_16x16x32_bf16 v[58:61], v[232:235], v[220:223], v[58:61]
	v_mfma_f32_16x16x32_bf16 v[62:65], v[236:239], v[220:223], v[62:65]
	s_waitcnt lgkmcnt(3)
	v_mfma_f32_16x16x32_bf16 v[74:77], v[240:243], v[208:211], v[74:77]
	s_waitcnt lgkmcnt(2)
	v_mfma_f32_16x16x32_bf16 v[78:81], v[244:247], v[208:211], v[78:81]
	s_waitcnt lgkmcnt(1)
	v_mfma_f32_16x16x32_bf16 v[82:85], v[248:251], v[208:211], v[82:85]
	s_waitcnt lgkmcnt(0)
	v_mfma_f32_16x16x32_bf16 v[86:89], v[156:159], v[208:211], v[86:89]
	v_mfma_f32_16x16x32_bf16 v[90:93], v[240:243], v[212:215], v[90:93]
	v_mfma_f32_16x16x32_bf16 v[94:97], v[244:247], v[212:215], v[94:97]
	v_mfma_f32_16x16x32_bf16 v[98:101], v[248:251], v[212:215], v[98:101]
	v_mfma_f32_16x16x32_bf16 v[102:105], v[156:159], v[212:215], v[102:105]
	v_mfma_f32_16x16x32_bf16 v[106:109], v[240:243], v[216:219], v[106:109]
	v_mfma_f32_16x16x32_bf16 v[110:113], v[244:247], v[216:219], v[110:113]
	v_mfma_f32_16x16x32_bf16 v[114:117], v[248:251], v[216:219], v[114:117]
	v_mfma_f32_16x16x32_bf16 v[118:121], v[156:159], v[216:219], v[118:121]
	v_mfma_f32_16x16x32_bf16 v[122:125], v[240:243], v[220:223], v[122:125]
	v_mfma_f32_16x16x32_bf16 v[126:129], v[244:247], v[220:223], v[126:129]
	v_mfma_f32_16x16x32_bf16 v[130:133], v[248:251], v[220:223], v[130:133]
	v_mfma_f32_16x16x32_bf16 v[134:137], v[156:159], v[220:223], v[134:137]
	s_mov_b32 s46, 9

; DI int TID() { int t = (int)__builtin_amdgcn_workitem_id_x(); asm volatile("" : "+v"(t)); return t; }
; #define BLOAD(A_, B_, kt) do { _Pragma("unroll") for (int i = 0; i < 4; ++i) { \
;     A_[i] = *(const u32x4*)((const char*)Ap + (aoff + (unsigned)(32 * i * lda + (kt) * 64) * 2u)); B_[i] = *(const u32x4*)((const char*)Wt + (woff + (unsigned)(32 * i * K + (kt) * 64) * 2u)); } } while (0)
; #define BLOAD(A_, B_, kt) do { _Pragma("unroll") for (int i = 0; i < 4; ++i) { \
;     A_[i] = *(const u32x4*)((const char*)Ap + (aoff + (unsigned)(32 * i * lda + (kt) * 64) * 2u)); B_[i] = *(const u32x4*)((const char*)Wt + (woff + (unsigned)(32 * i * K + (kt) * 64) * 2u)); } } while (0)
; #define BSTORE(A_, B_, buf) do { _Pragma("unroll") for (int i = 0; i < 4; ++i) { \
;     *(u32x4*)&As[(buf) * GBUF + (srow + 32 * i) * LDT + sc8] = A_[i]; \
;     *(u32x4*)&Bs[(buf) * GBUF + (srow + 32 * i) * LDT + sc8] = B_[i]; } } while (0)
; template <int NK>
; DI void gemm_run(PF& pf, const u16* __restrict__ Ap, int lda, const u16* __restrict__ Wt, f32x16 (&acc)[2][2], char* smem) {
;     ...
;   __builtin_amdgcn_s_setprio(0);
;   __syncthreads();
;   BSTORE(pf.a0, pf.b0, 0);
;   BLOAD(pf.a0, pf.b0, 2);
;   __syncthreads();
; #pragma unroll
;   for (int kt = 0; kt < nk; kt += 2) {
;     BCOMP(0);
;     BSTORE(pf.a1, pf.b1, 1);
;     if (kt + 3 < nk) BLOAD(pf.a1, pf.b1, kt + 3);
;     __syncthreads();
;     BCOMP(1);
;     if (kt + 2 < nk) { BSTORE(pf.a0, pf.b0, 0); if (kt + 4 < nk) BLOAD(pf.a0, pf.b0, kt + 4); }
;     __syncthreads();
;   }
; DI void tile_outproj(const Params& p, int l, const Chunk& ck, int tile, int next, PF& pf, char* smem) {
;   float* Cs = (float*)smem;
;   const int tid = TID(); const int mi = tile & (MTN - 1), ni = tile >> MTS; const int m0 = mi * 128, n0 = ni * 128;
;   f32x16 acc[2][2]; zero_acc(acc);
;   { const u16* Ap; const u16* Wt; outproj_ptrs(p, l, tile, Ap, Wt); gemm_run<16>(pf, Ap, 1024, Wt, acc, smem); }
.LBB1_255:
	s_add_i32 s41, s35, s78
	s_cmpk_gt_i32 s41, 0x1ff
	s_cselect_b64 s[24:25], -1, 0
	s_cmpk_lt_i32 s41, 0x200
	s_cselect_b32 s0, s41, -1
	s_and_b32 s27, s34, 0xfe0000
	s_and_b32 s26, s35, 0xffffff80
	s_lshl_b32 s26, s26, 1
	s_lshr_b32 s27, s27, 4
	s_add_u32 s28, s16, s27
	v_mov_b32_e32 v0, v172
	s_addc_u32 s29, s17, 0
	s_ashr_i32 s27, s26, 31
	s_lshl_b64 s[30:31], s[26:27], 6
	s_add_u32 s30, s36, s30
	s_addc_u32 s31, s37, s31
	s_setprio 0
	s_waitcnt lgkmcnt(0)
	v_and_b32_e32 v150, 63, v172
	v_lshrrev_b32_e32 v151, 6, v172
	v_bfe_u32 v152, v150, 4, 2
	v_lshrrev_b32_e32 v153, 1, v152
	v_xor_b32_e32 v152, v152, v153
	v_and_b32_e32 v152, 1, v152
	v_lshl_or_b32 v152, v152, 1, v153
	v_xor_b32_e32 v152, v152, v150
	v_and_b32_e32 v152, 3, v152
	v_lshlrev_b32_e32 v152, 4, v152
	v_lshrrev_b32_e32 v153, 2, v150
	v_lshl_add_u32 v143, v151, 5, v153
	v_lshl_add_u32 v143, v143, 6, v152
	v_mov_b32_e32 v144, v143
	v_lshl_add_u32 v145, v151, 6, v153
	v_lshl_add_u32 v145, v145, 6, v152
	v_mov_b32_e32 v146, v145
	v_mov_b32_e32 v147, v145
	v_mov_b32_e32 v148, v145
	v_readfirstlane_b32 s42, v151
	s_lshl_b32 s43, s42, 12
	s_lshl_b32 s42, s42, 11
	s_add_u32 s43, s43, 0x2000
	v_bfe_u32 v152, v150, 2, 2
	v_lshrrev_b32_e32 v153, 1, v152
	v_xor_b32_e32 v152, v152, v153
	v_and_b32_e32 v152, 1, v152
	v_lshl_or_b32 v152, v152, 1, v153
	v_lshrrev_b32_e32 v153, 4, v150
	v_xor_b32_e32 v152, v152, v153
	v_lshlrev_b32_e32 v152, 4, v152
	v_and_b32_e32 v150, 15, v150
	v_lshl_add_u32 v150, v150, 6, v152
	v_lshrrev_b32_e32 v152, 1, v151
	v_and_b32_e32 v153, 1, v151
	v_lshl_add_u32 v126, v152, 12, v150
	v_lshl_add_u32 v128, v153, 12, v150
	v_add_u32_e32 v128, 0x2000, v128
	s_barrier
	s_add_u32 m0, s42, 0x0
	s_nop 0
	global_load_lds_dwordx4 v143, s[28:29]
	global_load_lds_dwordx4 v144, s[28:29] offset:1024
	s_add_u32 m0, s43, 0x0
	s_nop 0
	global_load_lds_dwordx4 v145, s[30:31]
	global_load_lds_dwordx4 v146, s[30:31] offset:1024
	global_load_lds_dwordx4 v147, s[30:31] offset:2048
	global_load_lds_dwordx4 v148, s[30:31] offset:3072
	s_add_u32 m0, s42, 0x6000
	s_add_u32 s28, s28, 0x100000
	s_addc_u32 s29, s29, 0
	global_load_lds_dwordx4 v143, s[28:29]
	global_load_lds_dwordx4 v144, s[28:29] offset:1024
	s_add_u32 m0, s43, 0x6000
	s_add_u32 s30, s30, 0x10000
	s_addc_u32 s31, s31, 0
	global_load_lds_dwordx4 v145, s[30:31]
	global_load_lds_dwordx4 v146, s[30:31] offset:1024
	global_load_lds_dwordx4 v147, s[30:31] offset:2048
	global_load_lds_dwordx4 v148, s[30:31] offset:3072
	s_waitcnt vmcnt(6)
	s_barrier
	ds_read_b128 v[224:227], v126 offset:0
	ds_read_b128 v[240:243], v128 offset:0
	ds_read_b128 v[244:247], v128 offset:1024
	ds_read_b128 v[248:251], v128 offset:2048
	ds_read_b128 v[156:159], v128 offset:3072
	s_add_u32 m0, s42, 0xc000
	s_add_u32 s28, s28, 0x100000
	s_addc_u32 s29, s29, 0
	global_load_lds_dwordx4 v143, s[28:29]
	global_load_lds_dwordx4 v144, s[28:29] offset:1024
	s_add_u32 m0, s43, 0xc000
	s_add_u32 s30, s30, 0x10000
	s_addc_u32 s31, s31, 0
	global_load_lds_dwordx4 v145, s[30:31]
	global_load_lds_dwordx4 v146, s[30:31] offset:1024
	global_load_lds_dwordx4 v147, s[30:31] offset:2048
	global_load_lds_dwordx4 v148, s[30:31] offset:3072
	ds_read_b128 v[228:231], v126 offset:1024
	ds_read_b128 v[232:235], v126 offset:2048
	ds_read_b128 v[236:239], v126 offset:3072
	ds_read_b128 v[160:163], v128 offset:8192
	ds_read_b128 v[164:167], v128 offset:9216
	ds_read_b128 v[168:171], v128 offset:10240
	ds_read_b128 v[122:125], v128 offset:11264
	s_waitcnt lgkmcnt(10)
	v_mfma_f32_16x16x32_bf16 v[2:5], v[240:243], v[224:227], 0
	s_waitcnt lgkmcnt(9)
	v_mfma_f32_16x16x32_bf16 v[6:9], v[244:247], v[224:227], 0
	s_waitcnt lgkmcnt(8)
	v_mfma_f32_16x16x32_bf16 v[10:13], v[248:251], v[224:227], 0
	s_waitcnt lgkmcnt(7)
	v_mfma_f32_16x16x32_bf16 v[14:17], v[156:159], v[224:227], 0
	s_waitcnt lgkmcnt(6)
	v_mfma_f32_16x16x32_bf16 v[18:21], v[240:243], v[228:231], 0
	v_mfma_f32_16x16x32_bf16 v[22:25], v[244:247], v[228:231], 0
	v_mfma_f32_16x16x32_bf16 v[26:29], v[248:251], v[228:231], 0
	v_mfma_f32_16x16x32_bf16 v[30:33], v[156:159], v[228:231], 0
	s_waitcnt lgkmcnt(5)
	v_mfma_f32_16x16x32_bf16 v[34:37], v[240:243], v[232:235], 0
	v_mfma_f32_16x16x32_bf16 v[38:41], v[244:247], v[232:235], 0
	v_mfma_f32_16x16x32_bf16 v[42:45], v[248:251], v[232:235], 0
	v_mfma_f32_16x16x32_bf16 v[46:49], v[156:159], v[232:235], 0
	s_waitcnt lgkmcnt(4)
	v_mfma_f32_16x16x32_bf16 v[50:53], v[240:243], v[236:239], 0
	v_mfma_f32_16x16x32_bf16 v[54:57], v[244:247], v[236:239], 0
	v_mfma_f32_16x16x32_bf16 v[58:61], v[248:251], v[236:239], 0
	v_mfma_f32_16x16x32_bf16 v[62:65], v[156:159], v[236:239], 0
	s_waitcnt lgkmcnt(3)
	v_mfma_f32_16x16x32_bf16 v[74:77], v[160:163], v[224:227], 0
	s_waitcnt lgkmcnt(2)
	v_mfma_f32_16x16x32_bf16 v[78:81], v[164:167], v[224:227], 0
	s_waitcnt lgkmcnt(1)
	v_mfma_f32_16x16x32_bf16 v[82:85], v[168:171], v[224:227], 0
	s_waitcnt lgkmcnt(0)
	v_mfma_f32_16x16x32_bf16 v[86:89], v[122:125], v[224:227], 0
	v_mfma_f32_16x16x32_bf16 v[90:93], v[160:163], v[228:231], 0
	v_mfma_f32_16x16x32_bf16 v[94:97], v[164:167], v[228:231], 0
	v_mfma_f32_16x16x32_bf16 v[98:101], v[168:171], v[228:231], 0
	v_mfma_f32_16x16x32_bf16 v[102:105], v[122:125], v[228:231], 0
	v_mfma_f32_16x16x32_bf16 v[106:109], v[160:163], v[232:235], 0
	v_mfma_f32_16x16x32_bf16 v[110:113], v[164:167], v[232:235], 0
	v_mfma_f32_16x16x32_bf16 v[114:117], v[168:171], v[232:235], 0
	v_mfma_f32_16x16x32_bf16 v[118:121], v[122:125], v[232:235], 0
	v_mfma_f32_16x16x32_bf16 v[208:211], v[160:163], v[236:239], 0
	v_mfma_f32_16x16x32_bf16 v[212:215], v[164:167], v[236:239], 0
	v_mfma_f32_16x16x32_bf16 v[216:219], v[168:171], v[236:239], 0
	v_mfma_f32_16x16x32_bf16 v[220:223], v[122:125], v[236:239], 0
	s_waitcnt vmcnt(6)
	s_barrier
; #define BLOAD(A_, B_, kt) do { _Pragma("unroll") for (int i = 0; i < 4; ++i) { \
;     A_[i] = *(const u32x4*)((const char*)Ap + (aoff + (unsigned)(32 * i * lda + (kt) * 64) * 2u)); B_[i] = *(const u32x4*)((const char*)Wt + (woff + (unsigned)(32 * i * K + (kt) * 64) * 2u)); } } while (0)
; #define BLOAD(A_, B_, kt) do { _Pragma("unroll") for (int i = 0; i < 4; ++i) { \
;     A_[i] = *(const u32x4*)((const char*)Ap + (aoff + (unsigned)(32 * i * lda + (kt) * 64) * 2u)); B_[i] = *(const u32x4*)((const char*)Wt + (woff + (unsigned)(32 * i * K + (kt) * 64) * 2u)); } } while (0)
; #define BSTORE(A_, B_, buf) do { _Pragma("unroll") for (int i = 0; i < 4; ++i) { \
;     *(u32x4*)&As[(buf) * GBUF + (srow + 32 * i) * LDT + sc8] = A_[i]; \
;     *(u32x4*)&Bs[(buf) * GBUF + (srow + 32 * i) * LDT + sc8] = B_[i]; } } while (0)
; template <int NK>
; DI void gemm_run(PF& pf, const u16* __restrict__ Ap, int lda, const u16* __restrict__ Wt, f32x16 (&acc)[2][2], char* smem) {
;     ...
;   __builtin_amdgcn_s_setprio(0);
;   __syncthreads();
;   BSTORE(pf.a0, pf.b0, 0);
;   BLOAD(pf.a0, pf.b0, 2);
;   __syncthreads();
; #pragma unroll
;   for (int kt = 0; kt < nk; kt += 2) {
;     BCOMP(0);
;     BSTORE(pf.a1, pf.b1, 1);
;     if (kt + 3 < nk) BLOAD(pf.a1, pf.b1, kt + 3);
;     __syncthreads();
;     BCOMP(1);
;     if (kt + 2 < nk) { BSTORE(pf.a0, pf.b0, 0); if (kt + 4 < nk) BLOAD(pf.a0, pf.b0, kt + 4); }
;     __syncthreads();
;   }
	ds_read_b128 v[224:227], v126 offset:24576
	ds_read_b128 v[240:243], v128 offset:24576
	ds_read_b128 v[244:247], v128 offset:25600
	ds_read_b128 v[248:251], v128 offset:26624
	ds_read_b128 v[156:159], v128 offset:27648
	s_add_u32 m0, s42, 0x0
	s_add_u32 s28, s28, 0x100000
	s_addc_u32 s29, s29, 0
	global_load_lds_dwordx4 v143, s[28:29]
	global_load_lds_dwordx4 v144, s[28:29] offset:1024
	s_add_u32 m0, s43, 0x0
	s_add_u32 s30, s30, 0x10000
	s_addc_u32 s31, s31, 0
	global_load_lds_dwordx4 v145, s[30:31]
	global_load_lds_dwordx4 v146, s[30:31] offset:1024
	global_load_lds_dwordx4 v147, s[30:31] offset:2048
	global_load_lds_dwordx4 v148, s[30:31] offset:3072
	ds_read_b128 v[228:231], v126 offset:25600
	ds_read_b128 v[232:235], v126 offset:26624
	ds_read_b128 v[236:239], v126 offset:27648
	ds_read_b128 v[160:163], v128 offset:32768
	ds_read_b128 v[164:167], v128 offset:33792
	ds_read_b128 v[168:171], v128 offset:34816
	ds_read_b128 v[122:125], v128 offset:35840
	s_waitcnt lgkmcnt(10)
	v_mfma_f32_16x16x32_bf16 v[2:5], v[240:243], v[224:227], v[2:5]
	s_waitcnt lgkmcnt(9)
	v_mfma_f32_16x16x32_bf16 v[6:9], v[244:247], v[224:227], v[6:9]
	s_waitcnt lgkmcnt(8)
	v_mfma_f32_16x16x32_bf16 v[10:13], v[248:251], v[224:227], v[10:13]
	s_waitcnt lgkmcnt(7)
	v_mfma_f32_16x16x32_bf16 v[14:17], v[156:159], v[224:227], v[14:17]
	s_waitcnt lgkmcnt(6)
	v_mfma_f32_16x16x32_bf16 v[18:21], v[240:243], v[228:231], v[18:21]
	v_mfma_f32_16x16x32_bf16 v[22:25], v[244:247], v[228:231], v[22:25]
	v_mfma_f32_16x16x32_bf16 v[26:29], v[248:251], v[228:231], v[26:29]
	v_mfma_f32_16x16x32_bf16 v[30:33], v[156:159], v[228:231], v[30:33]
	s_waitcnt lgkmcnt(5)
	v_mfma_f32_16x16x32_bf16 v[34:37], v[240:243], v[232:235], v[34:37]
	v_mfma_f32_16x16x32_bf16 v[38:41], v[244:247], v[232:235], v[38:41]
	v_mfma_f32_16x16x32_bf16 v[42:45], v[248:251], v[232:235], v[42:45]
	v_mfma_f32_16x16x32_bf16 v[46:49], v[156:159], v[232:235], v[46:49]
	s_waitcnt lgkmcnt(4)
	v_mfma_f32_16x16x32_bf16 v[50:53], v[240:243], v[236:239], v[50:53]
	v_mfma_f32_16x16x32_bf16 v[54:57], v[244:247], v[236:239], v[54:57]
	v_mfma_f32_16x16x32_bf16 v[58:61], v[248:251], v[236:239], v[58:61]
	v_mfma_f32_16x16x32_bf16 v[62:65], v[156:159], v[236:239], v[62:65]
	s_waitcnt lgkmcnt(3)
	v_mfma_f32_16x16x32_bf16 v[74:77], v[160:163], v[224:227], v[74:77]
	s_waitcnt lgkmcnt(2)
	v_mfma_f32_16x16x32_bf16 v[78:81], v[164:167], v[224:227], v[78:81]
	s_waitcnt lgkmcnt(1)
	v_mfma_f32_16x16x32_bf16 v[82:85], v[168:171], v[224:227], v[82:85]
	s_waitcnt lgkmcnt(0)
	v_mfma_f32_16x16x32_bf16 v[86:89], v[122:125], v[224:227], v[86:89]
	v_mfma_f32_16x16x32_bf16 v[90:93], v[160:163], v[228:231], v[90:93]
	v_mfma_f32_16x16x32_bf16 v[94:97], v[164:167], v[228:231], v[94:97]
	v_mfma_f32_16x16x32_bf16 v[98:101], v[168:171], v[228:231], v[98:101]
	v_mfma_f32_16x16x32_bf16 v[102:105], v[122:125], v[228:231], v[102:105]
	v_mfma_f32_16x16x32_bf16 v[106:109], v[160:163], v[232:235], v[106:109]
	v_mfma_f32_16x16x32_bf16 v[110:113], v[164:167], v[232:235], v[110:113]
	v_mfma_f32_16x16x32_bf16 v[114:117], v[168:171], v[232:235], v[114:117]
	v_mfma_f32_16x16x32_bf16 v[118:121], v[122:125], v[232:235], v[118:121]
	v_mfma_f32_16x16x32_bf16 v[208:211], v[160:163], v[236:239], v[208:211]
	v_mfma_f32_16x16x32_bf16 v[212:215], v[164:167], v[236:239], v[212:215]
	v_mfma_f32_16x16x32_bf16 v[216:219], v[168:171], v[236:239], v[216:219]
	v_mfma_f32_16x16x32_bf16 v[220:223], v[122:125], v[236:239], v[220:223]
	s_waitcnt vmcnt(6)
	s_barrier
	ds_read_b128 v[224:227], v126 offset:49152
	ds_read_b128 v[240:243], v128 offset:49152
	ds_read_b128 v[244:247], v128 offset:50176
	ds_read_b128 v[248:251], v128 offset:51200
	ds_read_b128 v[156:159], v128 offset:52224
	s_add_u32 m0, s42, 0x6000
	s_add_u32 s28, s28, 0x100000
	s_addc_u32 s29, s29, 0
	global_load_lds_dwordx4 v143, s[28:29]
	global_load_lds_dwordx4 v144, s[28:29] offset:1024
	s_add_u32 m0, s43, 0x6000
	s_add_u32 s30, s30, 0x10000
	s_addc_u32 s31, s31, 0
	global_load_lds_dwordx4 v145, s[30:31]
	global_load_lds_dwordx4 v146, s[30:31] offset:1024
	global_load_lds_dwordx4 v147, s[30:31] offset:2048
	global_load_lds_dwordx4 v148, s[30:31] offset:3072
	ds_read_b128 v[228:231], v126 offset:50176
	ds_read_b128 v[232:235], v126 offset:51200
	ds_read_b128 v[236:239], v126 offset:52224
	ds_read_b128 v[160:163], v128 offset:57344
	ds_read_b128 v[164:167], v128 offset:58368
	ds_read_b128 v[168:171], v128 offset:59392
	ds_read_b128 v[122:125], v128 offset:60416
	s_waitcnt lgkmcnt(10)
	v_mfma_f32_16x16x32_bf16 v[2:5], v[240:243], v[224:227], v[2:5]
	s_waitcnt lgkmcnt(9)
	v_mfma_f32_16x16x32_bf16 v[6:9], v[244:247], v[224:227], v[6:9]
	s_waitcnt lgkmcnt(8)
	v_mfma_f32_16x16x32_bf16 v[10:13], v[248:251], v[224:227], v[10:13]
	s_waitcnt lgkmcnt(7)
	v_mfma_f32_16x16x32_bf16 v[14:17], v[156:159], v[224:227], v[14:17]
	s_waitcnt lgkmcnt(6)
	v_mfma_f32_16x16x32_bf16 v[18:21], v[240:243], v[228:231], v[18:21]
	v_mfma_f32_16x16x32_bf16 v[22:25], v[244:247], v[228:231], v[22:25]
	v_mfma_f32_16x16x32_bf16 v[26:29], v[248:251], v[228:231], v[26:29]
	v_mfma_f32_16x16x32_bf16 v[30:33], v[156:159], v[228:231], v[30:33]
	s_waitcnt lgkmcnt(5)
	v_mfma_f32_16x16x32_bf16 v[34:37], v[240:243], v[232:235], v[34:37]
	v_mfma_f32_16x16x32_bf16 v[38:41], v[244:247], v[232:235], v[38:41]
	v_mfma_f32_16x16x32_bf16 v[42:45], v[248:251], v[232:235], v[42:45]
	v_mfma_f32_16x16x32_bf16 v[46:49], v[156:159], v[232:235], v[46:49]
	s_waitcnt lgkmcnt(4)
	v_mfma_f32_16x16x32_bf16 v[50:53], v[240:243], v[236:239], v[50:53]
	v_mfma_f32_16x16x32_bf16 v[54:57], v[244:247], v[236:239], v[54:57]
	v_mfma_f32_16x16x32_bf16 v[58:61], v[248:251], v[236:239], v[58:61]
	v_mfma_f32_16x16x32_bf16 v[62:65], v[156:159], v[236:239], v[62:65]
	s_waitcnt lgkmcnt(3)
	v_mfma_f32_16x16x32_bf16 v[74:77], v[160:163], v[224:227], v[74:77]
	s_waitcnt lgkmcnt(2)
	v_mfma_f32_16x16x32_bf16 v[78:81], v[164:167], v[224:227], v[78:81]
	s_waitcnt lgkmcnt(1)
	v_mfma_f32_16x16x32_bf16 v[82:85], v[168:171], v[224:227], v[82:85]
	s_waitcnt lgkmcnt(0)
	v_mfma_f32_16x16x32_bf16 v[86:89], v[122:125], v[224:227], v[86:89]
	v_mfma_f32_16x16x32_bf16 v[90:93], v[160:163], v[228:231], v[90:93]
	v_mfma_f32_16x16x32_bf16 v[94:97], v[164:167], v[228:231], v[94:97]
	v_mfma_f32_16x16x32_bf16 v[98:101], v[168:171], v[228:231], v[98:101]
	v_mfma_f32_16x16x32_bf16 v[102:105], v[122:125], v[228:231], v[102:105]
	v_mfma_f32_16x16x32_bf16 v[106:109], v[160:163], v[232:235], v[106:109]
	v_mfma_f32_16x16x32_bf16 v[110:113], v[164:167], v[232:235], v[110:113]
	v_mfma_f32_16x16x32_bf16 v[114:117], v[168:171], v[232:235], v[114:117]
	v_mfma_f32_16x16x32_bf16 v[118:121], v[122:125], v[232:235], v[118:121]
	v_mfma_f32_16x16x32_bf16 v[208:211], v[160:163], v[236:239], v[208:211]
	v_mfma_f32_16x16x32_bf16 v[212:215], v[164:167], v[236:239], v[212:215]
	v_mfma_f32_16x16x32_bf16 v[216:219], v[168:171], v[236:239], v[216:219]
	v_mfma_f32_16x16x32_bf16 v[220:223], v[122:125], v[236:239], v[220:223]
	s_mov_b32 s46, 9

; #define BLOAD(A_, B_, kt) do { _Pragma("unroll") for (int i = 0; i < 4; ++i) { \
;     A_[i] = *(const u32x4*)((const char*)Ap + (aoff + (unsigned)(32 * i * lda + (kt) * 64) * 2u)); B_[i] = *(const u32x4*)((const char*)Wt + (woff + (unsigned)(32 * i * K + (kt) * 64) * 2u)); } } while (0)
; #define BLOAD(A_, B_, kt) do { _Pragma("unroll") for (int i = 0; i < 4; ++i) { \
;     A_[i] = *(const u32x4*)((const char*)Ap + (aoff + (unsigned)(32 * i * lda + (kt) * 64) * 2u)); B_[i] = *(const u32x4*)((const char*)Wt + (woff + (unsigned)(32 * i * K + (kt) * 64) * 2u)); } } while (0)
; #define BSTORE(A_, B_, buf) do { _Pragma("unroll") for (int i = 0; i < 4; ++i) { \
;     *(u32x4*)&As[(buf) * GBUF + (srow + 32 * i) * LDT + sc8] = A_[i]; \
;     *(u32x4*)&Bs[(buf) * GBUF + (srow + 32 * i) * LDT + sc8] = B_[i]; } } while (0)
; template <bool ROWNORM, int NK>
; DI void gemm_main_bf(const u16* __restrict__ Ap, int lda, const u16* __restrict__ Wt, f32x16 (&acc)[2][2], char* smem, float* rinv_s) {
;     ...
;   __builtin_amdgcn_s_setprio(0);
;   BLOAD(a0, b0, 0); BLOAD(a1, b1, 1);
;   __syncthreads();
;   BSTORE(a0, b0, 0);
;   BLOAD(a0, b0, 2);
;   __syncthreads();
; #pragma unroll
;   for (int kt = 0; kt < nk; kt += 2) {
;     BCOMP(0);
;     BSTORE(a1, b1, 1);
;     if (kt + 3 < nk) BLOAD(a1, b1, kt + 3);
;     __syncthreads();
;     BCOMP(1);
;     if (kt + 2 < nk) { BSTORE(a0, b0, 0); if (kt + 4 < nk) BLOAD(a0, b0, kt + 4); }
;     __syncthreads();
;   }
; DI void tile_branch(const Params& p, int l, int tile, char* smem) {
;     ...
;   for (int br = 0; br < 3; ++br) {
;     unsigned gpk[2][2][8];
;     {
;       f32x16 accg[2][2]; zero_acc(accg);
;       gemm_main_bf<false, 16>((const u16*)(p.ws + OFF_XB) + (size_t)m0 * 1024, 1024,
;                               (const u16*)(p.ws + OFF_WIN + l * SZ_WIN) + (size_t)(5760 + br * 1024 + n0) * 1024, accg, smem, nullptr);
.Lbr_loop:
	s_waitcnt vmcnt(8)
	s_barrier
	ds_read_b128 v[208:211], v240 offset:0
	ds_read_b128 v[224:227], v241 offset:0
	ds_read_b128 v[228:231], v241 offset:1024
	ds_read_b128 v[232:235], v241 offset:2048
	ds_read_b128 v[236:239], v241 offset:3072
	s_add_u32 m0, s52, 0xc000
	s_add_u32 s28, s28, 0x100000
	s_addc_u32 s29, s29, 0
	global_load_lds_dwordx4 v251, s[28:29]
	global_load_lds_dwordx4 v251, s[28:29] offset:1024
	s_add_u32 m0, s53, 0xc000
	s_add_u32 s30, s30, 0x30000
	s_addc_u32 s31, s31, 0
	global_load_lds_dwordx4 v251, s[30:31]
	global_load_lds_dwordx4 v251, s[30:31] offset:1024
	ds_read_b128 v[212:215], v240 offset:1024
	ds_read_b128 v[216:219], v240 offset:2048
	ds_read_b128 v[220:223], v240 offset:3072
	s_waitcnt lgkmcnt(6)
	v_mfma_f32_16x16x32_bf16 v[2:5], v[224:227], v[208:211], 0
	s_waitcnt lgkmcnt(5)
	v_mfma_f32_16x16x32_bf16 v[6:9], v[228:231], v[208:211], 0
	s_waitcnt lgkmcnt(4)
	v_mfma_f32_16x16x32_bf16 v[10:13], v[232:235], v[208:211], 0
	s_waitcnt lgkmcnt(3)
	v_mfma_f32_16x16x32_bf16 v[14:17], v[236:239], v[208:211], 0
	s_waitcnt lgkmcnt(2)
	v_mfma_f32_16x16x32_bf16 v[18:21], v[224:227], v[212:215], 0
	v_mfma_f32_16x16x32_bf16 v[22:25], v[228:231], v[212:215], 0
	v_mfma_f32_16x16x32_bf16 v[26:29], v[232:235], v[212:215], 0
	v_mfma_f32_16x16x32_bf16 v[30:33], v[236:239], v[212:215], 0
	s_waitcnt lgkmcnt(1)
	v_mfma_f32_16x16x32_bf16 v[34:37], v[224:227], v[216:219], 0
	v_mfma_f32_16x16x32_bf16 v[38:41], v[228:231], v[216:219], 0
	v_mfma_f32_16x16x32_bf16 v[42:45], v[232:235], v[216:219], 0
	v_mfma_f32_16x16x32_bf16 v[46:49], v[236:239], v[216:219], 0
	s_waitcnt lgkmcnt(0)
	v_mfma_f32_16x16x32_bf16 v[50:53], v[224:227], v[220:223], 0
	v_mfma_f32_16x16x32_bf16 v[54:57], v[228:231], v[220:223], 0
	v_mfma_f32_16x16x32_bf16 v[58:61], v[232:235], v[220:223], 0
	v_mfma_f32_16x16x32_bf16 v[62:65], v[236:239], v[220:223], 0
	s_waitcnt vmcnt(8)
	s_barrier
	ds_read_b128 v[208:211], v240 offset:16384
	ds_read_b128 v[224:227], v241 offset:16384
	ds_read_b128 v[228:231], v241 offset:17408
	ds_read_b128 v[232:235], v241 offset:18432
	ds_read_b128 v[236:239], v241 offset:19456
	s_add_u32 m0, s52, 0x0
	s_add_u32 s28, s28, 0x100000
	s_addc_u32 s29, s29, 0
	global_load_lds_dwordx4 v251, s[28:29]
	global_load_lds_dwordx4 v251, s[28:29] offset:1024
	s_add_u32 m0, s53, 0x0
	s_add_u32 s30, s30, 0x30000
	s_addc_u32 s31, s31, 0
	global_load_lds_dwordx4 v251, s[30:31]
	global_load_lds_dwordx4 v251, s[30:31] offset:1024
	ds_read_b128 v[212:215], v240 offset:17408
	ds_read_b128 v[216:219], v240 offset:18432
	ds_read_b128 v[220:223], v240 offset:19456
	s_waitcnt lgkmcnt(6)
	v_mfma_f32_16x16x32_bf16 v[2:5], v[224:227], v[208:211], v[2:5]
	s_waitcnt lgkmcnt(5)
	v_mfma_f32_16x16x32_bf16 v[6:9], v[228:231], v[208:211], v[6:9]
	s_waitcnt lgkmcnt(4)
	v_mfma_f32_16x16x32_bf16 v[10:13], v[232:235], v[208:211], v[10:13]
	s_waitcnt lgkmcnt(3)
	v_mfma_f32_16x16x32_bf16 v[14:17], v[236:239], v[208:211], v[14:17]
	s_waitcnt lgkmcnt(2)
	v_mfma_f32_16x16x32_bf16 v[18:21], v[224:227], v[212:215], v[18:21]
	v_mfma_f32_16x16x32_bf16 v[22:25], v[228:231], v[212:215], v[22:25]
	v_mfma_f32_16x16x32_bf16 v[26:29], v[232:235], v[212:215], v[26:29]
	v_mfma_f32_16x16x32_bf16 v[30:33], v[236:239], v[212:215], v[30:33]
	s_waitcnt lgkmcnt(1)
	v_mfma_f32_16x16x32_bf16 v[34:37], v[224:227], v[216:219], v[34:37]
	v_mfma_f32_16x16x32_bf16 v[38:41], v[228:231], v[216:219], v[38:41]
	v_mfma_f32_16x16x32_bf16 v[42:45], v[232:235], v[216:219], v[42:45]
	v_mfma_f32_16x16x32_bf16 v[46:49], v[236:239], v[216:219], v[46:49]
	s_waitcnt lgkmcnt(0)
	v_mfma_f32_16x16x32_bf16 v[50:53], v[224:227], v[220:223], v[50:53]
	v_mfma_f32_16x16x32_bf16 v[54:57], v[228:231], v[220:223], v[54:57]
	v_mfma_f32_16x16x32_bf16 v[58:61], v[232:235], v[220:223], v[58:61]
	v_mfma_f32_16x16x32_bf16 v[62:65], v[236:239], v[220:223], v[62:65]
	s_waitcnt vmcnt(8)
	s_barrier
	ds_read_b128 v[208:211], v240 offset:32768
	ds_read_b128 v[224:227], v241 offset:32768
	ds_read_b128 v[228:231], v241 offset:33792
	ds_read_b128 v[232:235], v241 offset:34816
	ds_read_b128 v[236:239], v241 offset:35840
	s_add_u32 m0, s52, 0x4000
	s_add_u32 s28, s28, 0x100000
	s_addc_u32 s29, s29, 0
	global_load_lds_dwordx4 v251, s[28:29]
	global_load_lds_dwordx4 v251, s[28:29] offset:1024
	s_add_u32 m0, s53, 0x4000
	s_add_u32 s30, s30, 0x30000
	s_addc_u32 s31, s31, 0
	global_load_lds_dwordx4 v251, s[30:31]
	global_load_lds_dwordx4 v251, s[30:31] offset:1024
	ds_read_b128 v[212:215], v240 offset:33792
	ds_read_b128 v[216:219], v240 offset:34816
	ds_read_b128 v[220:223], v240 offset:35840
	s_waitcnt lgkmcnt(6)
	v_mfma_f32_16x16x32_bf16 v[2:5], v[224:227], v[208:211], v[2:5]
	s_waitcnt lgkmcnt(5)
	v_mfma_f32_16x16x32_bf16 v[6:9], v[228:231], v[208:211], v[6:9]
	s_waitcnt lgkmcnt(4)
	v_mfma_f32_16x16x32_bf16 v[10:13], v[232:235], v[208:211], v[10:13]
	s_waitcnt lgkmcnt(3)
	v_mfma_f32_16x16x32_bf16 v[14:17], v[236:239], v[208:211], v[14:17]
	s_waitcnt lgkmcnt(2)
	v_mfma_f32_16x16x32_bf16 v[18:21], v[224:227], v[212:215], v[18:21]
	v_mfma_f32_16x16x32_bf16 v[22:25], v[228:231], v[212:215], v[22:25]
	v_mfma_f32_16x16x32_bf16 v[26:29], v[232:235], v[212:215], v[26:29]
	v_mfma_f32_16x16x32_bf16 v[30:33], v[236:239], v[212:215], v[30:33]
	s_waitcnt lgkmcnt(1)
	v_mfma_f32_16x16x32_bf16 v[34:37], v[224:227], v[216:219], v[34:37]
	v_mfma_f32_16x16x32_bf16 v[38:41], v[228:231], v[216:219], v[38:41]
	v_mfma_f32_16x16x32_bf16 v[42:45], v[232:235], v[216:219], v[42:45]
	v_mfma_f32_16x16x32_bf16 v[46:49], v[236:239], v[216:219], v[46:49]
	s_waitcnt lgkmcnt(0)
	v_mfma_f32_16x16x32_bf16 v[50:53], v[224:227], v[220:223], v[50:53]
	v_mfma_f32_16x16x32_bf16 v[54:57], v[228:231], v[220:223], v[54:57]
	v_mfma_f32_16x16x32_bf16 v[58:61], v[232:235], v[220:223], v[58:61]
	v_mfma_f32_16x16x32_bf16 v[62:65], v[236:239], v[220:223], v[62:65]
	s_waitcnt vmcnt(8)
	s_barrier
; #define BLOAD(A_, B_, kt) do { _Pragma("unroll") for (int i = 0; i < 4; ++i) { \
;     A_[i] = *(const u32x4*)((const char*)Ap + (aoff + (unsigned)(32 * i * lda + (kt) * 64) * 2u)); B_[i] = *(const u32x4*)((const char*)Wt + (woff + (unsigned)(32 * i * K + (kt) * 64) * 2u)); } } while (0)
; #define BLOAD(A_, B_, kt) do { _Pragma("unroll") for (int i = 0; i < 4; ++i) { \
;     A_[i] = *(const u32x4*)((const char*)Ap + (aoff + (unsigned)(32 * i * lda + (kt) * 64) * 2u)); B_[i] = *(const u32x4*)((const char*)Wt + (woff + (unsigned)(32 * i * K + (kt) * 64) * 2u)); } } while (0)
; #define BSTORE(A_, B_, buf) do { _Pragma("unroll") for (int i = 0; i < 4; ++i) { \
;     *(u32x4*)&As[(buf) * GBUF + (srow + 32 * i) * LDT + sc8] = A_[i]; \
;     *(u32x4*)&Bs[(buf) * GBUF + (srow + 32 * i) * LDT + sc8] = B_[i]; } } while (0)
; template <bool ROWNORM, int NK>
; DI void gemm_main_bf(const u16* __restrict__ Ap, int lda, const u16* __restrict__ Wt, f32x16 (&acc)[2][2], char* smem, float* rinv_s) {
;     ...
;   __builtin_amdgcn_s_setprio(0);
;   BLOAD(a0, b0, 0); BLOAD(a1, b1, 1);
;   __syncthreads();
;   BSTORE(a0, b0, 0);
;   BLOAD(a0, b0, 2);
;   __syncthreads();
; #pragma unroll
;   for (int kt = 0; kt < nk; kt += 2) {
;     BCOMP(0);
;     BSTORE(a1, b1, 1);
;     if (kt + 3 < nk) BLOAD(a1, b1, kt + 3);
;     __syncthreads();
;     BCOMP(1);
;     if (kt + 2 < nk) { BSTORE(a0, b0, 0); if (kt + 4 < nk) BLOAD(a0, b0, kt + 4); }
;     __syncthreads();
	ds_read_b128 v[208:211], v240 offset:49152
	ds_read_b128 v[224:227], v241 offset:49152
	ds_read_b128 v[228:231], v241 offset:50176
	ds_read_b128 v[232:235], v241 offset:51200
	ds_read_b128 v[236:239], v241 offset:52224
	s_add_u32 m0, s52, 0x8000
	s_add_u32 s28, s28, 0x100000
	s_addc_u32 s29, s29, 0
	global_load_lds_dwordx4 v251, s[28:29]
	global_load_lds_dwordx4 v251, s[28:29] offset:1024
	s_add_u32 m0, s53, 0x8000
	s_add_u32 s30, s30, 0x30000
	s_addc_u32 s31, s31, 0
	global_load_lds_dwordx4 v251, s[30:31]
	global_load_lds_dwordx4 v251, s[30:31] offset:1024
	ds_read_b128 v[212:215], v240 offset:50176
	ds_read_b128 v[216:219], v240 offset:51200
	ds_read_b128 v[220:223], v240 offset:52224
	s_waitcnt lgkmcnt(6)
	v_mfma_f32_16x16x32_bf16 v[2:5], v[224:227], v[208:211], v[2:5]
	s_waitcnt lgkmcnt(5)
	v_mfma_f32_16x16x32_bf16 v[6:9], v[228:231], v[208:211], v[6:9]
	s_waitcnt lgkmcnt(4)
	v_mfma_f32_16x16x32_bf16 v[10:13], v[232:235], v[208:211], v[10:13]
	s_waitcnt lgkmcnt(3)
	v_mfma_f32_16x16x32_bf16 v[14:17], v[236:239], v[208:211], v[14:17]
	s_waitcnt lgkmcnt(2)
	v_mfma_f32_16x16x32_bf16 v[18:21], v[224:227], v[212:215], v[18:21]
	v_mfma_f32_16x16x32_bf16 v[22:25], v[228:231], v[212:215], v[22:25]
	v_mfma_f32_16x16x32_bf16 v[26:29], v[232:235], v[212:215], v[26:29]
	v_mfma_f32_16x16x32_bf16 v[30:33], v[236:239], v[212:215], v[30:33]
	s_waitcnt lgkmcnt(1)
	v_mfma_f32_16x16x32_bf16 v[34:37], v[224:227], v[216:219], v[34:37]
	v_mfma_f32_16x16x32_bf16 v[38:41], v[228:231], v[216:219], v[38:41]
	v_mfma_f32_16x16x32_bf16 v[42:45], v[232:235], v[216:219], v[42:45]
	v_mfma_f32_16x16x32_bf16 v[46:49], v[236:239], v[216:219], v[46:49]
	s_waitcnt lgkmcnt(0)
	v_mfma_f32_16x16x32_bf16 v[50:53], v[224:227], v[220:223], v[50:53]
	v_mfma_f32_16x16x32_bf16 v[54:57], v[228:231], v[220:223], v[54:57]
	v_mfma_f32_16x16x32_bf16 v[58:61], v[232:235], v[220:223], v[58:61]
	v_mfma_f32_16x16x32_bf16 v[62:65], v[236:239], v[220:223], v[62:65]
	s_mov_b32 s74, 6
.Lbr_gate_k:
	s_waitcnt vmcnt(8)
	s_barrier
	ds_read_b128 v[208:211], v240 offset:0
	ds_read_b128 v[224:227], v241 offset:0
	ds_read_b128 v[228:231], v241 offset:1024
	ds_read_b128 v[232:235], v241 offset:2048
	ds_read_b128 v[236:239], v241 offset:3072
	s_add_u32 m0, s52, 0xc000
	s_add_u32 s28, s28, 0x100000
	s_addc_u32 s29, s29, 0
	global_load_lds_dwordx4 v251, s[28:29]
	global_load_lds_dwordx4 v251, s[28:29] offset:1024
	s_add_u32 m0, s53, 0xc000
	s_add_u32 s30, s30, 0x30000
	s_addc_u32 s31, s31, 0
	global_load_lds_dwordx4 v251, s[30:31]
	global_load_lds_dwordx4 v251, s[30:31] offset:1024
	ds_read_b128 v[212:215], v240 offset:1024
	ds_read_b128 v[216:219], v240 offset:2048
	ds_read_b128 v[220:223], v240 offset:3072
	s_waitcnt lgkmcnt(6)
	v_mfma_f32_16x16x32_bf16 v[2:5], v[224:227], v[208:211], v[2:5]
	s_waitcnt lgkmcnt(5)
	v_mfma_f32_16x16x32_bf16 v[6:9], v[228:231], v[208:211], v[6:9]
	s_waitcnt lgkmcnt(4)
	v_mfma_f32_16x16x32_bf16 v[10:13], v[232:235], v[208:211], v[10:13]
	s_waitcnt lgkmcnt(3)
	v_mfma_f32_16x16x32_bf16 v[14:17], v[236:239], v[208:211], v[14:17]
	s_waitcnt lgkmcnt(2)
	v_mfma_f32_16x16x32_bf16 v[18:21], v[224:227], v[212:215], v[18:21]
	v_mfma_f32_16x16x32_bf16 v[22:25], v[228:231], v[212:215], v[22:25]
	v_mfma_f32_16x16x32_bf16 v[26:29], v[232:235], v[212:215], v[26:29]
	v_mfma_f32_16x16x32_bf16 v[30:33], v[236:239], v[212:215], v[30:33]
	s_waitcnt lgkmcnt(1)
	v_mfma_f32_16x16x32_bf16 v[34:37], v[224:227], v[216:219], v[34:37]
	v_mfma_f32_16x16x32_bf16 v[38:41], v[228:231], v[216:219], v[38:41]
	v_mfma_f32_16x16x32_bf16 v[42:45], v[232:235], v[216:219], v[42:45]
	v_mfma_f32_16x16x32_bf16 v[46:49], v[236:239], v[216:219], v[46:49]
	s_waitcnt lgkmcnt(0)
	v_mfma_f32_16x16x32_bf16 v[50:53], v[224:227], v[220:223], v[50:53]
	v_mfma_f32_16x16x32_bf16 v[54:57], v[228:231], v[220:223], v[54:57]
	v_mfma_f32_16x16x32_bf16 v[58:61], v[232:235], v[220:223], v[58:61]
	v_mfma_f32_16x16x32_bf16 v[62:65], v[236:239], v[220:223], v[62:65]
	s_waitcnt vmcnt(8)
	s_barrier
	ds_read_b128 v[208:211], v240 offset:16384
	ds_read_b128 v[224:227], v241 offset:16384
	ds_read_b128 v[228:231], v241 offset:17408
	ds_read_b128 v[232:235], v241 offset:18432
	ds_read_b128 v[236:239], v241 offset:19456
	s_add_u32 m0, s52, 0x0
	s_add_u32 s28, s28, 0x100000
	s_addc_u32 s29, s29, 0
	global_load_lds_dwordx4 v251, s[28:29]
	global_load_lds_dwordx4 v251, s[28:29] offset:1024
	s_add_u32 m0, s53, 0x0
	s_add_u32 s30, s30, 0x30000
	s_addc_u32 s31, s31, 0
	global_load_lds_dwordx4 v251, s[30:31]
	global_load_lds_dwordx4 v251, s[30:31] offset:1024
	ds_read_b128 v[212:215], v240 offset:17408
	ds_read_b128 v[216:219], v240 offset:18432
	ds_read_b128 v[220:223], v240 offset:19456
	s_waitcnt lgkmcnt(6)
	v_mfma_f32_16x16x32_bf16 v[2:5], v[224:227], v[208:211], v[2:5]
	s_waitcnt lgkmcnt(5)
	v_mfma_f32_16x16x32_bf16 v[6:9], v[228:231], v[208:211], v[6:9]
	s_waitcnt lgkmcnt(4)
	v_mfma_f32_16x16x32_bf16 v[10:13], v[232:235], v[208:211], v[10:13]
	s_waitcnt lgkmcnt(3)
	v_mfma_f32_16x16x32_bf16 v[14:17], v[236:239], v[208:211], v[14:17]
	s_waitcnt lgkmcnt(2)
	v_mfma_f32_16x16x32_bf16 v[18:21], v[224:227], v[212:215], v[18:21]
	v_mfma_f32_16x16x32_bf16 v[22:25], v[228:231], v[212:215], v[22:25]
	v_mfma_f32_16x16x32_bf16 v[26:29], v[232:235], v[212:215], v[26:29]
	v_mfma_f32_16x16x32_bf16 v[30:33], v[236:239], v[212:215], v[30:33]
	s_waitcnt lgkmcnt(1)
	v_mfma_f32_16x16x32_bf16 v[34:37], v[224:227], v[216:219], v[34:37]
	v_mfma_f32_16x16x32_bf16 v[38:41], v[228:231], v[216:219], v[38:41]
	v_mfma_f32_16x16x32_bf16 v[42:45], v[232:235], v[216:219], v[42:45]
	v_mfma_f32_16x16x32_bf16 v[46:49], v[236:239], v[216:219], v[46:49]
	s_waitcnt lgkmcnt(0)
	v_mfma_f32_16x16x32_bf16 v[50:53], v[224:227], v[220:223], v[50:53]
	v_mfma_f32_16x16x32_bf16 v[54:57], v[228:231], v[220:223], v[54:57]
	v_mfma_f32_16x16x32_bf16 v[58:61], v[232:235], v[220:223], v[58:61]
	v_mfma_f32_16x16x32_bf16 v[62:65], v[236:239], v[220:223], v[62:65]
	s_waitcnt vmcnt(8)
	s_barrier
; #define BLOAD(A_, B_, kt) do { _Pragma("unroll") for (int i = 0; i < 4; ++i) { \
;     A_[i] = *(const u32x4*)((const char*)Ap + (aoff + (unsigned)(32 * i * lda + (kt) * 64) * 2u)); B_[i] = *(const u32x4*)((const char*)Wt + (woff + (unsigned)(32 * i * K + (kt) * 64) * 2u)); } } while (0)
; #define BLOAD(A_, B_, kt) do { _Pragma("unroll") for (int i = 0; i < 4; ++i) { \
;     A_[i] = *(const u32x4*)((const char*)Ap + (aoff + (unsigned)(32 * i * lda + (kt) * 64) * 2u)); B_[i] = *(const u32x4*)((const char*)Wt + (woff + (unsigned)(32 * i * K + (kt) * 64) * 2u)); } } while (0)
; #define BSTORE(A_, B_, buf) do { _Pragma("unroll") for (int i = 0; i < 4; ++i) { \
;     *(u32x4*)&As[(buf) * GBUF + (srow + 32 * i) * LDT + sc8] = A_[i]; \
;     *(u32x4*)&Bs[(buf) * GBUF + (srow + 32 * i) * LDT + sc8] = B_[i]; } } while (0)
; template <bool ROWNORM, int NK>
; DI void gemm_main_bf(const u16* __restrict__ Ap, int lda, const u16* __restrict__ Wt, f32x16 (&acc)[2][2], char* smem, float* rinv_s) {
;     ...
;   __builtin_amdgcn_s_setprio(0);
;   BLOAD(a0, b0, 0); BLOAD(a1, b1, 1);
;   __syncthreads();
;   BSTORE(a0, b0, 0);
;   BLOAD(a0, b0, 2);
;   __syncthreads();
; #pragma unroll
;   for (int kt = 0; kt < nk; kt += 2) {
;     BCOMP(0);
;     BSTORE(a1, b1, 1);
;     if (kt + 3 < nk) BLOAD(a1, b1, kt + 3);
;     __syncthreads();
;     BCOMP(1);
;     if (kt + 2 < nk) { BSTORE(a0, b0, 0); if (kt + 4 < nk) BLOAD(a0, b0, kt + 4); }
;     __syncthreads();
	ds_read_b128 v[208:211], v240 offset:32768
	ds_read_b128 v[224:227], v241 offset:32768
	ds_read_b128 v[228:231], v241 offset:33792
	ds_read_b128 v[232:235], v241 offset:34816
	ds_read_b128 v[236:239], v241 offset:35840
	s_add_u32 m0, s52, 0x4000
	s_add_u32 s28, s28, 0x100000
	s_addc_u32 s29, s29, 0
	global_load_lds_dwordx4 v251, s[28:29]
	global_load_lds_dwordx4 v251, s[28:29] offset:1024
	s_add_u32 m0, s53, 0x4000
	s_add_u32 s30, s30, 0x30000
	s_addc_u32 s31, s31, 0
	global_load_lds_dwordx4 v251, s[30:31]
	global_load_lds_dwordx4 v251, s[30:31] offset:1024
	ds_read_b128 v[212:215], v240 offset:33792
	ds_read_b128 v[216:219], v240 offset:34816
	ds_read_b128 v[220:223], v240 offset:35840
	s_waitcnt lgkmcnt(6)
	v_mfma_f32_16x16x32_bf16 v[2:5], v[224:227], v[208:211], v[2:5]
	s_waitcnt lgkmcnt(5)
	v_mfma_f32_16x16x32_bf16 v[6:9], v[228:231], v[208:211], v[6:9]
	s_waitcnt lgkmcnt(4)
	v_mfma_f32_16x16x32_bf16 v[10:13], v[232:235], v[208:211], v[10:13]
	s_waitcnt lgkmcnt(3)
	v_mfma_f32_16x16x32_bf16 v[14:17], v[236:239], v[208:211], v[14:17]
	s_waitcnt lgkmcnt(2)
	v_mfma_f32_16x16x32_bf16 v[18:21], v[224:227], v[212:215], v[18:21]
	v_mfma_f32_16x16x32_bf16 v[22:25], v[228:231], v[212:215], v[22:25]
	v_mfma_f32_16x16x32_bf16 v[26:29], v[232:235], v[212:215], v[26:29]
	v_mfma_f32_16x16x32_bf16 v[30:33], v[236:239], v[212:215], v[30:33]
	s_waitcnt lgkmcnt(1)
	v_mfma_f32_16x16x32_bf16 v[34:37], v[224:227], v[216:219], v[34:37]
	v_mfma_f32_16x16x32_bf16 v[38:41], v[228:231], v[216:219], v[38:41]
	v_mfma_f32_16x16x32_bf16 v[42:45], v[232:235], v[216:219], v[42:45]
	v_mfma_f32_16x16x32_bf16 v[46:49], v[236:239], v[216:219], v[46:49]
	s_waitcnt lgkmcnt(0)
	v_mfma_f32_16x16x32_bf16 v[50:53], v[224:227], v[220:223], v[50:53]
	v_mfma_f32_16x16x32_bf16 v[54:57], v[228:231], v[220:223], v[54:57]
	v_mfma_f32_16x16x32_bf16 v[58:61], v[232:235], v[220:223], v[58:61]
	v_mfma_f32_16x16x32_bf16 v[62:65], v[236:239], v[220:223], v[62:65]
	s_waitcnt vmcnt(8)
	s_barrier
	ds_read_b128 v[208:211], v240 offset:49152
	ds_read_b128 v[224:227], v241 offset:49152
	ds_read_b128 v[228:231], v241 offset:50176
	ds_read_b128 v[232:235], v241 offset:51200
	ds_read_b128 v[236:239], v241 offset:52224
	s_add_u32 m0, s52, 0x8000
	s_add_u32 s28, s28, 0x100000
	s_addc_u32 s29, s29, 0
	global_load_lds_dwordx4 v251, s[28:29]
	global_load_lds_dwordx4 v251, s[28:29] offset:1024
	s_add_u32 m0, s53, 0x8000
	s_add_u32 s30, s30, 0x30000
	s_addc_u32 s31, s31, 0
	global_load_lds_dwordx4 v251, s[30:31]
	global_load_lds_dwordx4 v251, s[30:31] offset:1024
	ds_read_b128 v[212:215], v240 offset:50176
	ds_read_b128 v[216:219], v240 offset:51200
	ds_read_b128 v[220:223], v240 offset:52224
	s_waitcnt lgkmcnt(6)
	v_mfma_f32_16x16x32_bf16 v[2:5], v[224:227], v[208:211], v[2:5]
	s_waitcnt lgkmcnt(5)
	v_mfma_f32_16x16x32_bf16 v[6:9], v[228:231], v[208:211], v[6:9]
	s_waitcnt lgkmcnt(4)
	v_mfma_f32_16x16x32_bf16 v[10:13], v[232:235], v[208:211], v[10:13]
	s_waitcnt lgkmcnt(3)
	v_mfma_f32_16x16x32_bf16 v[14:17], v[236:239], v[208:211], v[14:17]
	s_waitcnt lgkmcnt(2)
	v_mfma_f32_16x16x32_bf16 v[18:21], v[224:227], v[212:215], v[18:21]
	v_mfma_f32_16x16x32_bf16 v[22:25], v[228:231], v[212:215], v[22:25]
	v_mfma_f32_16x16x32_bf16 v[26:29], v[232:235], v[212:215], v[26:29]
	v_mfma_f32_16x16x32_bf16 v[30:33], v[236:239], v[212:215], v[30:33]
	s_waitcnt lgkmcnt(1)
	v_mfma_f32_16x16x32_bf16 v[34:37], v[224:227], v[216:219], v[34:37]
	v_mfma_f32_16x16x32_bf16 v[38:41], v[228:231], v[216:219], v[38:41]
	v_mfma_f32_16x16x32_bf16 v[42:45], v[232:235], v[216:219], v[42:45]
	v_mfma_f32_16x16x32_bf16 v[46:49], v[236:239], v[216:219], v[46:49]
	s_waitcnt lgkmcnt(0)
	v_mfma_f32_16x16x32_bf16 v[50:53], v[224:227], v[220:223], v[50:53]
	v_mfma_f32_16x16x32_bf16 v[54:57], v[228:231], v[220:223], v[54:57]
	v_mfma_f32_16x16x32_bf16 v[58:61], v[232:235], v[220:223], v[58:61]
	v_mfma_f32_16x16x32_bf16 v[62:65], v[236:239], v[220:223], v[62:65]
	s_sub_u32 s74, s74, 1
	s_cmp_lg_u32 s74, 0
	s_cbranch_scc1 .Lbr_gate_k
	s_waitcnt vmcnt(8)
	s_barrier
	ds_read_b128 v[208:211], v240 offset:0
	ds_read_b128 v[224:227], v241 offset:0
	ds_read_b128 v[228:231], v241 offset:1024
	ds_read_b128 v[232:235], v241 offset:2048
	ds_read_b128 v[236:239], v241 offset:3072
	s_add_u32 m0, s52, 0xc000
	s_add_u32 s28, s28, 0x100000
	s_addc_u32 s29, s29, 0
	global_load_lds_dwordx4 v251, s[28:29]
	global_load_lds_dwordx4 v251, s[28:29] offset:1024
	s_add_u32 m0, s53, 0xc000
	s_add_u32 s30, s30, 0x30000
	s_addc_u32 s31, s31, 0
	global_load_lds_dwordx4 v251, s[30:31]
	global_load_lds_dwordx4 v251, s[30:31] offset:1024
	ds_read_b128 v[212:215], v240 offset:1024
	ds_read_b128 v[216:219], v240 offset:2048
	ds_read_b128 v[220:223], v240 offset:3072
	s_waitcnt lgkmcnt(6)
	v_mfma_f32_16x16x32_bf16 v[2:5], v[224:227], v[208:211], v[2:5]
	s_waitcnt lgkmcnt(5)
	v_mfma_f32_16x16x32_bf16 v[6:9], v[228:231], v[208:211], v[6:9]
	s_waitcnt lgkmcnt(4)
	v_mfma_f32_16x16x32_bf16 v[10:13], v[232:235], v[208:211], v[10:13]
	s_waitcnt lgkmcnt(3)
	v_mfma_f32_16x16x32_bf16 v[14:17], v[236:239], v[208:211], v[14:17]
	s_waitcnt lgkmcnt(2)
	v_mfma_f32_16x16x32_bf16 v[18:21], v[224:227], v[212:215], v[18:21]
	v_mfma_f32_16x16x32_bf16 v[22:25], v[228:231], v[212:215], v[22:25]
	v_mfma_f32_16x16x32_bf16 v[26:29], v[232:235], v[212:215], v[26:29]
	v_mfma_f32_16x16x32_bf16 v[30:33], v[236:239], v[212:215], v[30:33]
	s_waitcnt lgkmcnt(1)
	v_mfma_f32_16x16x32_bf16 v[34:37], v[224:227], v[216:219], v[34:37]
	v_mfma_f32_16x16x32_bf16 v[38:41], v[228:231], v[216:219], v[38:41]
	v_mfma_f32_16x16x32_bf16 v[42:45], v[232:235], v[216:219], v[42:45]
	v_mfma_f32_16x16x32_bf16 v[46:49], v[236:239], v[216:219], v[46:49]
	s_waitcnt lgkmcnt(0)
	v_mfma_f32_16x16x32_bf16 v[50:53], v[224:227], v[220:223], v[50:53]
	v_mfma_f32_16x16x32_bf16 v[54:57], v[228:231], v[220:223], v[54:57]
	v_mfma_f32_16x16x32_bf16 v[58:61], v[232:235], v[220:223], v[58:61]
	v_mfma_f32_16x16x32_bf16 v[62:65], v[236:239], v[220:223], v[62:65]
	s_waitcnt vmcnt(8)
	s_barrier
; #define BLOAD(A_, B_, kt) do { _Pragma("unroll") for (int i = 0; i < 4; ++i) { \
;     A_[i] = *(const u32x4*)((const char*)Ap + (aoff + (unsigned)(32 * i * lda + (kt) * 64) * 2u)); B_[i] = *(const u32x4*)((const char*)Wt + (woff + (unsigned)(32 * i * K + (kt) * 64) * 2u)); } } while (0)
; #define BLOAD(A_, B_, kt) do { _Pragma("unroll") for (int i = 0; i < 4; ++i) { \
;     A_[i] = *(const u32x4*)((const char*)Ap + (aoff + (unsigned)(32 * i * lda + (kt) * 64) * 2u)); B_[i] = *(const u32x4*)((const char*)Wt + (woff + (unsigned)(32 * i * K + (kt) * 64) * 2u)); } } while (0)
; #define BSTORE(A_, B_, buf) do { _Pragma("unroll") for (int i = 0; i < 4; ++i) { \
;     *(u32x4*)&As[(buf) * GBUF + (srow + 32 * i) * LDT + sc8] = A_[i]; \
;     *(u32x4*)&Bs[(buf) * GBUF + (srow + 32 * i) * LDT + sc8] = B_[i]; } } while (0)
; template <bool ROWNORM, int NK>
; DI void gemm_main_bf(const u16* __restrict__ Ap, int lda, const u16* __restrict__ Wt, f32x16 (&acc)[2][2], char* smem, float* rinv_s) {
;     ...
;   __builtin_amdgcn_s_setprio(0);
;   BLOAD(a0, b0, 0); BLOAD(a1, b1, 1);
;   __syncthreads();
;   BSTORE(a0, b0, 0);
;   BLOAD(a0, b0, 2);
;   __syncthreads();
; #pragma unroll
;   for (int kt = 0; kt < nk; kt += 2) {
;     BCOMP(0);
;     BSTORE(a1, b1, 1);
;     if (kt + 3 < nk) BLOAD(a1, b1, kt + 3);
;     __syncthreads();
;     BCOMP(1);
;     if (kt + 2 < nk) { BSTORE(a0, b0, 0); if (kt + 4 < nk) BLOAD(a0, b0, kt + 4); }
;     __syncthreads();
; DI void tile_branch(const Params& p, int l, int tile, char* smem) {
;     ...
;       __syncthreads();
; #pragma unroll
;       for (int mt = 0; mt < 2; ++mt)
; #pragma unroll
;         for (int g4 = 0; g4 < 4; ++g4) {
;           const f32x4 r4 = *(const f32x4*)&rinv_s[wm * 64 + mt * 32 + 8 * g4 + 4 * hi];
	ds_read_b128 v[208:211], v240 offset:16384
	ds_read_b128 v[224:227], v241 offset:16384
	ds_read_b128 v[228:231], v241 offset:17408
	ds_read_b128 v[232:235], v241 offset:18432
	ds_read_b128 v[236:239], v241 offset:19456
	ds_read_b128 v[212:215], v240 offset:17408
	ds_read_b128 v[216:219], v240 offset:18432
	ds_read_b128 v[220:223], v240 offset:19456
	s_waitcnt lgkmcnt(6)
	v_mfma_f32_16x16x32_bf16 v[2:5], v[224:227], v[208:211], v[2:5]
	s_waitcnt lgkmcnt(5)
	v_mfma_f32_16x16x32_bf16 v[6:9], v[228:231], v[208:211], v[6:9]
	s_waitcnt lgkmcnt(4)
	v_mfma_f32_16x16x32_bf16 v[10:13], v[232:235], v[208:211], v[10:13]
	s_waitcnt lgkmcnt(3)
	v_mfma_f32_16x16x32_bf16 v[14:17], v[236:239], v[208:211], v[14:17]
	s_waitcnt lgkmcnt(2)
	v_mfma_f32_16x16x32_bf16 v[18:21], v[224:227], v[212:215], v[18:21]
	v_mfma_f32_16x16x32_bf16 v[22:25], v[228:231], v[212:215], v[22:25]
	v_mfma_f32_16x16x32_bf16 v[26:29], v[232:235], v[212:215], v[26:29]
	v_mfma_f32_16x16x32_bf16 v[30:33], v[236:239], v[212:215], v[30:33]
	s_waitcnt lgkmcnt(1)
	v_mfma_f32_16x16x32_bf16 v[34:37], v[224:227], v[216:219], v[34:37]
	v_mfma_f32_16x16x32_bf16 v[38:41], v[228:231], v[216:219], v[38:41]
	v_mfma_f32_16x16x32_bf16 v[42:45], v[232:235], v[216:219], v[42:45]
	v_mfma_f32_16x16x32_bf16 v[46:49], v[236:239], v[216:219], v[46:49]
	s_waitcnt lgkmcnt(0)
	v_mfma_f32_16x16x32_bf16 v[50:53], v[224:227], v[220:223], v[50:53]
	v_mfma_f32_16x16x32_bf16 v[54:57], v[228:231], v[220:223], v[54:57]
	v_mfma_f32_16x16x32_bf16 v[58:61], v[232:235], v[220:223], v[58:61]
	v_mfma_f32_16x16x32_bf16 v[62:65], v[236:239], v[220:223], v[62:65]
	s_waitcnt vmcnt(4)
	s_barrier
	ds_read_b128 v[208:211], v240 offset:32768
	ds_read_b128 v[224:227], v241 offset:32768
	ds_read_b128 v[228:231], v241 offset:33792
	ds_read_b128 v[232:235], v241 offset:34816
	ds_read_b128 v[236:239], v241 offset:35840
	ds_read_b128 v[212:215], v240 offset:33792
	ds_read_b128 v[216:219], v240 offset:34816
	ds_read_b128 v[220:223], v240 offset:35840
	s_waitcnt lgkmcnt(6)
	v_mfma_f32_16x16x32_bf16 v[2:5], v[224:227], v[208:211], v[2:5]
	s_waitcnt lgkmcnt(5)
	v_mfma_f32_16x16x32_bf16 v[6:9], v[228:231], v[208:211], v[6:9]
	s_waitcnt lgkmcnt(4)
	v_mfma_f32_16x16x32_bf16 v[10:13], v[232:235], v[208:211], v[10:13]
	s_waitcnt lgkmcnt(3)
	v_mfma_f32_16x16x32_bf16 v[14:17], v[236:239], v[208:211], v[14:17]
	s_waitcnt lgkmcnt(2)
	v_mfma_f32_16x16x32_bf16 v[18:21], v[224:227], v[212:215], v[18:21]
	v_mfma_f32_16x16x32_bf16 v[22:25], v[228:231], v[212:215], v[22:25]
	v_mfma_f32_16x16x32_bf16 v[26:29], v[232:235], v[212:215], v[26:29]
	v_mfma_f32_16x16x32_bf16 v[30:33], v[236:239], v[212:215], v[30:33]
	s_waitcnt lgkmcnt(1)
	v_mfma_f32_16x16x32_bf16 v[34:37], v[224:227], v[216:219], v[34:37]
	v_mfma_f32_16x16x32_bf16 v[38:41], v[228:231], v[216:219], v[38:41]
	v_mfma_f32_16x16x32_bf16 v[42:45], v[232:235], v[216:219], v[42:45]
	v_mfma_f32_16x16x32_bf16 v[46:49], v[236:239], v[216:219], v[46:49]
	s_waitcnt lgkmcnt(0)
	v_mfma_f32_16x16x32_bf16 v[50:53], v[224:227], v[220:223], v[50:53]
	v_mfma_f32_16x16x32_bf16 v[54:57], v[228:231], v[220:223], v[54:57]
	v_mfma_f32_16x16x32_bf16 v[58:61], v[232:235], v[220:223], v[58:61]
	v_mfma_f32_16x16x32_bf16 v[62:65], v[236:239], v[220:223], v[62:65]
	s_waitcnt vmcnt(0)
	s_barrier
	ds_read_b128 v[208:211], v240 offset:49152
	ds_read_b128 v[224:227], v241 offset:49152
	ds_read_b128 v[228:231], v241 offset:50176
	ds_read_b128 v[232:235], v241 offset:51200
	ds_read_b128 v[236:239], v241 offset:52224
	ds_read_b128 v[212:215], v240 offset:50176
	ds_read_b128 v[216:219], v240 offset:51200
	ds_read_b128 v[220:223], v240 offset:52224
	s_waitcnt lgkmcnt(6)
	v_mfma_f32_16x16x32_bf16 v[2:5], v[224:227], v[208:211], v[2:5]
	s_waitcnt lgkmcnt(5)
	v_mfma_f32_16x16x32_bf16 v[6:9], v[228:231], v[208:211], v[6:9]
	s_waitcnt lgkmcnt(4)
	v_mfma_f32_16x16x32_bf16 v[10:13], v[232:235], v[208:211], v[10:13]
	s_waitcnt lgkmcnt(3)
	v_mfma_f32_16x16x32_bf16 v[14:17], v[236:239], v[208:211], v[14:17]
	s_waitcnt lgkmcnt(2)
	v_mfma_f32_16x16x32_bf16 v[18:21], v[224:227], v[212:215], v[18:21]
	v_mfma_f32_16x16x32_bf16 v[22:25], v[228:231], v[212:215], v[22:25]
	v_mfma_f32_16x16x32_bf16 v[26:29], v[232:235], v[212:215], v[26:29]
	v_mfma_f32_16x16x32_bf16 v[30:33], v[236:239], v[212:215], v[30:33]
	s_waitcnt lgkmcnt(1)
	v_mfma_f32_16x16x32_bf16 v[34:37], v[224:227], v[216:219], v[34:37]
	v_mfma_f32_16x16x32_bf16 v[38:41], v[228:231], v[216:219], v[38:41]
	v_mfma_f32_16x16x32_bf16 v[42:45], v[232:235], v[216:219], v[42:45]
	v_mfma_f32_16x16x32_bf16 v[46:49], v[236:239], v[216:219], v[46:49]
	s_waitcnt lgkmcnt(0)
	v_mfma_f32_16x16x32_bf16 v[50:53], v[224:227], v[220:223], v[50:53]
	v_mfma_f32_16x16x32_bf16 v[54:57], v[228:231], v[220:223], v[54:57]
	v_mfma_f32_16x16x32_bf16 v[58:61], v[232:235], v[220:223], v[58:61]
	v_mfma_f32_16x16x32_bf16 v[62:65], v[236:239], v[220:223], v[62:65]
	s_mov_b64 s[28:29], s[48:49]
	s_mov_b64 s[30:31], s[50:51]
	ds_read_b32 v162, v250 offset:0
	ds_read_b32 v163, v250 offset:64
	ds_read_b32 v164, v250 offset:128
	ds_read_b32 v165, v250 offset:192
	s_waitcnt lgkmcnt(0)
; DI unsigned pk2(float a, float b) { f2_t v = {a, b}; bf2_t r = __builtin_convertvector(v, bf2_t); return __builtin_bit_cast(unsigned, r); }
; DI void tile_branch(const Params& p, int l, int tile, char* smem) {
;     ...
; #pragma unroll
;       for (int mt = 0; mt < 2; ++mt)
; #pragma unroll
;         for (int g4 = 0; g4 < 4; ++g4) {
;           const f32x4 r4 = *(const f32x4*)&rinv_s[wm * 64 + mt * 32 + 8 * g4 + 4 * hi];
; #pragma unroll
;           for (int nt = 0; nt < 2; ++nt) {
;             const float s0 = 1.f / (1.f + __expf(-accg[mt][nt][4 * g4 + 0] * r4[0])), s1 = 1.f / (1.f + __expf(-accg[mt][nt][4 * g4 + 1] * r4[1]));
;             const float s2 = 1.f / (1.f + __expf(-accg[mt][nt][4 * g4 + 2] * r4[2])), s3 = 1.f / (1.f + __expf(-accg[mt][nt][4 * g4 + 3] * r4[3]));
;             gpk[mt][nt][2 * g4] = pk2(s0, s1); gpk[mt][nt][2 * g4 + 1] = pk2(s2, s3);
;           }
;         }
	v_mul_f32_e32 v162, 0xbfb8aa3b, v162
	v_mul_f32_e32 v163, 0xbfb8aa3b, v163
	v_mul_f32_e32 v164, 0xbfb8aa3b, v164
	v_mul_f32_e32 v165, 0xbfb8aa3b, v165
	v_mul_f32_e32 v166, v162, v2
	v_mul_f32_e32 v167, v162, v3
	v_mul_f32_e32 v168, v162, v4
	v_mul_f32_e32 v169, v162, v5
	v_exp_f32_e32 v166, v166
	v_exp_f32_e32 v167, v167
	v_exp_f32_e32 v168, v168
	v_exp_f32_e32 v169, v169
	v_add_f32_e32 v166, 1.0, v166
	v_add_f32_e32 v167, 1.0, v167
	v_add_f32_e32 v168, 1.0, v168
	v_add_f32_e32 v169, 1.0, v169
	v_rcp_f32_e32 v166, v166
	v_rcp_f32_e32 v167, v167
	v_rcp_f32_e32 v168, v168
	v_rcp_f32_e32 v169, v169
	v_cvt_pk_bf16_f32 v130, v166, v167
	v_cvt_pk_bf16_f32 v131, v168, v169
	v_mul_f32_e32 v166, v162, v6
	v_mul_f32_e32 v167, v162, v7
	v_mul_f32_e32 v168, v162, v8
	v_mul_f32_e32 v169, v162, v9
	v_exp_f32_e32 v166, v166
	v_exp_f32_e32 v167, v167
	v_exp_f32_e32 v168, v168
	v_exp_f32_e32 v169, v169
	v_add_f32_e32 v166, 1.0, v166
	v_add_f32_e32 v167, 1.0, v167
	v_add_f32_e32 v168, 1.0, v168
	v_add_f32_e32 v169, 1.0, v169
	v_rcp_f32_e32 v166, v166
	v_rcp_f32_e32 v167, v167
	v_rcp_f32_e32 v168, v168
	v_rcp_f32_e32 v169, v169
	v_cvt_pk_bf16_f32 v132, v166, v167
	v_cvt_pk_bf16_f32 v133, v168, v169
	v_mul_f32_e32 v166, v162, v10
	v_mul_f32_e32 v167, v162, v11
	v_mul_f32_e32 v168, v162, v12
	v_mul_f32_e32 v169, v162, v13
	v_exp_f32_e32 v166, v166
	v_exp_f32_e32 v167, v167
	v_exp_f32_e32 v168, v168
	v_exp_f32_e32 v169, v169
	v_add_f32_e32 v166, 1.0, v166
	v_add_f32_e32 v167, 1.0, v167
	v_add_f32_e32 v168, 1.0, v168
	v_add_f32_e32 v169, 1.0, v169
	v_rcp_f32_e32 v166, v166
	v_rcp_f32_e32 v167, v167
	v_rcp_f32_e32 v168, v168
	v_rcp_f32_e32 v169, v169
	v_cvt_pk_bf16_f32 v134, v166, v167
	v_cvt_pk_bf16_f32 v135, v168, v169
	v_mul_f32_e32 v166, v162, v14
	v_mul_f32_e32 v167, v162, v15
	v_mul_f32_e32 v168, v162, v16
	v_mul_f32_e32 v169, v162, v17
	v_exp_f32_e32 v166, v166
	v_exp_f32_e32 v167, v167
	v_exp_f32_e32 v168, v168
	v_exp_f32_e32 v169, v169
	v_add_f32_e32 v166, 1.0, v166
	v_add_f32_e32 v167, 1.0, v167
	v_add_f32_e32 v168, 1.0, v168
	v_add_f32_e32 v169, 1.0, v169
	v_rcp_f32_e32 v166, v166
	v_rcp_f32_e32 v167, v167
	v_rcp_f32_e32 v168, v168
	v_rcp_f32_e32 v169, v169
	v_cvt_pk_bf16_f32 v136, v166, v167
	v_cvt_pk_bf16_f32 v137, v168, v169
	v_mul_f32_e32 v166, v163, v18
	v_mul_f32_e32 v167, v163, v19
	v_mul_f32_e32 v168, v163, v20
	v_mul_f32_e32 v169, v163, v21
	v_exp_f32_e32 v166, v166
	v_exp_f32_e32 v167, v167
	v_exp_f32_e32 v168, v168
	v_exp_f32_e32 v169, v169
	v_add_f32_e32 v166, 1.0, v166
	v_add_f32_e32 v167, 1.0, v167
	v_add_f32_e32 v168, 1.0, v168
	v_add_f32_e32 v169, 1.0, v169
	v_rcp_f32_e32 v166, v166
	v_rcp_f32_e32 v167, v167
	v_rcp_f32_e32 v168, v168
	v_rcp_f32_e32 v169, v169
	v_cvt_pk_bf16_f32 v138, v166, v167
	v_cvt_pk_bf16_f32 v139, v168, v169
	v_mul_f32_e32 v166, v163, v22
	v_mul_f32_e32 v167, v163, v23
	v_mul_f32_e32 v168, v163, v24
	v_mul_f32_e32 v169, v163, v25
	v_exp_f32_e32 v166, v166
	v_exp_f32_e32 v167, v167
	v_exp_f32_e32 v168, v168
	v_exp_f32_e32 v169, v169
	v_add_f32_e32 v166, 1.0, v166
	v_add_f32_e32 v167, 1.0, v167
	v_add_f32_e32 v168, 1.0, v168
	v_add_f32_e32 v169, 1.0, v169
	v_rcp_f32_e32 v166, v166
	v_rcp_f32_e32 v167, v167
	v_rcp_f32_e32 v168, v168
	v_rcp_f32_e32 v169, v169
	v_cvt_pk_bf16_f32 v140, v166, v167
	v_cvt_pk_bf16_f32 v141, v168, v169
	v_mul_f32_e32 v166, v163, v26
	v_mul_f32_e32 v167, v163, v27
	v_mul_f32_e32 v168, v163, v28
	v_mul_f32_e32 v169, v163, v29
	v_exp_f32_e32 v166, v166
	v_exp_f32_e32 v167, v167
	v_exp_f32_e32 v168, v168
	v_exp_f32_e32 v169, v169
	v_add_f32_e32 v166, 1.0, v166
	v_add_f32_e32 v167, 1.0, v167
	v_add_f32_e32 v168, 1.0, v168
	v_add_f32_e32 v169, 1.0, v169
	v_rcp_f32_e32 v166, v166
	v_rcp_f32_e32 v167, v167
	v_rcp_f32_e32 v168, v168
	v_rcp_f32_e32 v169, v169
	v_cvt_pk_bf16_f32 v142, v166, v167
	v_cvt_pk_bf16_f32 v143, v168, v169
	v_mul_f32_e32 v166, v163, v30
	v_mul_f32_e32 v167, v163, v31
	v_mul_f32_e32 v168, v163, v32
	v_mul_f32_e32 v169, v163, v33
	v_exp_f32_e32 v166, v166
	v_exp_f32_e32 v167, v167
	v_exp_f32_e32 v168, v168
	v_exp_f32_e32 v169, v169
	v_add_f32_e32 v166, 1.0, v166
	v_add_f32_e32 v167, 1.0, v167
	v_add_f32_e32 v168, 1.0, v168
	v_add_f32_e32 v169, 1.0, v169
	v_rcp_f32_e32 v166, v166
	v_rcp_f32_e32 v167, v167
	v_rcp_f32_e32 v168, v168
	v_rcp_f32_e32 v169, v169
	v_cvt_pk_bf16_f32 v144, v166, v167
	v_cvt_pk_bf16_f32 v145, v168, v169
	v_mul_f32_e32 v166, v164, v34
	v_mul_f32_e32 v167, v164, v35
	v_mul_f32_e32 v168, v164, v36
	v_mul_f32_e32 v169, v164, v37
	v_exp_f32_e32 v166, v166
	v_exp_f32_e32 v167, v167
	v_exp_f32_e32 v168, v168
	v_exp_f32_e32 v169, v169
	v_add_f32_e32 v166, 1.0, v166
	v_add_f32_e32 v167, 1.0, v167
	v_add_f32_e32 v168, 1.0, v168
	v_add_f32_e32 v169, 1.0, v169
	v_rcp_f32_e32 v166, v166
	v_rcp_f32_e32 v167, v167
	v_rcp_f32_e32 v168, v168
	v_rcp_f32_e32 v169, v169
	v_cvt_pk_bf16_f32 v146, v166, v167
	v_cvt_pk_bf16_f32 v147, v168, v169
	v_mul_f32_e32 v166, v164, v38
	v_mul_f32_e32 v167, v164, v39
	v_mul_f32_e32 v168, v164, v40
	v_mul_f32_e32 v169, v164, v41
	v_exp_f32_e32 v166, v166
	v_exp_f32_e32 v167, v167
	v_exp_f32_e32 v168, v168
	v_exp_f32_e32 v169, v169
	v_add_f32_e32 v166, 1.0, v166
	v_add_f32_e32 v167, 1.0, v167
	v_add_f32_e32 v168, 1.0, v168
	v_add_f32_e32 v169, 1.0, v169
	v_rcp_f32_e32 v166, v166
	v_rcp_f32_e32 v167, v167
	v_rcp_f32_e32 v168, v168
	v_rcp_f32_e32 v169, v169
	v_cvt_pk_bf16_f32 v148, v166, v167
	v_cvt_pk_bf16_f32 v149, v168, v169
	v_mul_f32_e32 v166, v164, v42
	v_mul_f32_e32 v167, v164, v43
	v_mul_f32_e32 v168, v164, v44
	v_mul_f32_e32 v169, v164, v45
	v_exp_f32_e32 v166, v166
	v_exp_f32_e32 v167, v167
	v_exp_f32_e32 v168, v168
	v_exp_f32_e32 v169, v169
; DI unsigned pk2(float a, float b) { f2_t v = {a, b}; bf2_t r = __builtin_convertvector(v, bf2_t); return __builtin_bit_cast(unsigned, r); }
; #define BLOAD(A_, B_, kt) do { _Pragma("unroll") for (int i = 0; i < 4; ++i) { \
;     A_[i] = *(const u32x4*)((const char*)Ap + (aoff + (unsigned)(32 * i * lda + (kt) * 64) * 2u)); B_[i] = *(const u32x4*)((const char*)Wt + (woff + (unsigned)(32 * i * K + (kt) * 64) * 2u)); } } while (0)
; #define BLOAD(A_, B_, kt) do { _Pragma("unroll") for (int i = 0; i < 4; ++i) { \
;     A_[i] = *(const u32x4*)((const char*)Ap + (aoff + (unsigned)(32 * i * lda + (kt) * 64) * 2u)); B_[i] = *(const u32x4*)((const char*)Wt + (woff + (unsigned)(32 * i * K + (kt) * 64) * 2u)); } } while (0)
; #define BSTORE(A_, B_, buf) do { _Pragma("unroll") for (int i = 0; i < 4; ++i) { \
;     *(u32x4*)&As[(buf) * GBUF + (srow + 32 * i) * LDT + sc8] = A_[i]; \
;     *(u32x4*)&Bs[(buf) * GBUF + (srow + 32 * i) * LDT + sc8] = B_[i]; } } while (0)
; template <bool ROWNORM, int NK>
; DI void gemm_main_bf(const u16* __restrict__ Ap, int lda, const u16* __restrict__ Wt, f32x16 (&acc)[2][2], char* smem, float* rinv_s) {
;     ...
;   __builtin_amdgcn_s_setprio(0);
;   BLOAD(a0, b0, 0); BLOAD(a1, b1, 1);
;   __syncthreads();
;   BSTORE(a0, b0, 0);
;   BLOAD(a0, b0, 2);
;   __syncthreads();
; #pragma unroll
;   for (int kt = 0; kt < nk; kt += 2) {
;     BCOMP(0);
; DI void tile_branch(const Params& p, int l, int tile, char* smem) {
;     ...
;             const float s0 = 1.f / (1.f + __expf(-accg[mt][nt][4 * g4 + 0] * r4[0])), s1 = 1.f / (1.f + __expf(-accg[mt][nt][4 * g4 + 1] * r4[1]));
;             const float s2 = 1.f / (1.f + __expf(-accg[mt][nt][4 * g4 + 2] * r4[2])), s3 = 1.f / (1.f + __expf(-accg[mt][nt][4 * g4 + 3] * r4[3]));
;             gpk[mt][nt][2 * g4] = pk2(s0, s1); gpk[mt][nt][2 * g4 + 1] = pk2(s2, s3);
;           }
;         }
;     }
;     f32x16 acc[2][2]; zero_acc(acc);
;     gemm_main_bf<false, 8>((const u16*)(p.ws + OFF_BR) + (size_t)(br * CT + m0) * 512, 512,
;                             (const u16*)(p.ws + OFF_WBR + (l * 3 + br) * SZ_WBR) + (size_t)n0 * 512, acc, smem, nullptr);
	v_add_f32_e32 v166, 1.0, v166
	v_add_f32_e32 v167, 1.0, v167
	v_add_f32_e32 v168, 1.0, v168
	v_add_f32_e32 v169, 1.0, v169
	v_rcp_f32_e32 v166, v166
	v_rcp_f32_e32 v167, v167
	v_rcp_f32_e32 v168, v168
	v_rcp_f32_e32 v169, v169
	v_cvt_pk_bf16_f32 v150, v166, v167
	v_cvt_pk_bf16_f32 v151, v168, v169
	v_mul_f32_e32 v166, v164, v46
	v_mul_f32_e32 v167, v164, v47
	v_mul_f32_e32 v168, v164, v48
	v_mul_f32_e32 v169, v164, v49
	v_exp_f32_e32 v166, v166
	v_exp_f32_e32 v167, v167
	v_exp_f32_e32 v168, v168
	v_exp_f32_e32 v169, v169
	v_add_f32_e32 v166, 1.0, v166
	v_add_f32_e32 v167, 1.0, v167
	v_add_f32_e32 v168, 1.0, v168
	v_add_f32_e32 v169, 1.0, v169
	v_rcp_f32_e32 v166, v166
	v_rcp_f32_e32 v167, v167
	v_rcp_f32_e32 v168, v168
	v_rcp_f32_e32 v169, v169
	v_cvt_pk_bf16_f32 v152, v166, v167
	v_cvt_pk_bf16_f32 v153, v168, v169
	v_mul_f32_e32 v166, v165, v50
	v_mul_f32_e32 v167, v165, v51
	v_mul_f32_e32 v168, v165, v52
	v_mul_f32_e32 v169, v165, v53
	v_exp_f32_e32 v166, v166
	v_exp_f32_e32 v167, v167
	v_exp_f32_e32 v168, v168
	v_exp_f32_e32 v169, v169
	v_add_f32_e32 v166, 1.0, v166
	v_add_f32_e32 v167, 1.0, v167
	v_add_f32_e32 v168, 1.0, v168
	v_add_f32_e32 v169, 1.0, v169
	v_rcp_f32_e32 v166, v166
	v_rcp_f32_e32 v167, v167
	v_rcp_f32_e32 v168, v168
	v_rcp_f32_e32 v169, v169
	v_cvt_pk_bf16_f32 v154, v166, v167
	v_cvt_pk_bf16_f32 v155, v168, v169
	v_mul_f32_e32 v166, v165, v54
	v_mul_f32_e32 v167, v165, v55
	v_mul_f32_e32 v168, v165, v56
	v_mul_f32_e32 v169, v165, v57
	v_exp_f32_e32 v166, v166
	v_exp_f32_e32 v167, v167
	v_exp_f32_e32 v168, v168
	v_exp_f32_e32 v169, v169
	v_add_f32_e32 v166, 1.0, v166
	v_add_f32_e32 v167, 1.0, v167
	v_add_f32_e32 v168, 1.0, v168
	v_add_f32_e32 v169, 1.0, v169
	v_rcp_f32_e32 v166, v166
	v_rcp_f32_e32 v167, v167
	v_rcp_f32_e32 v168, v168
	v_rcp_f32_e32 v169, v169
	v_cvt_pk_bf16_f32 v156, v166, v167
	v_cvt_pk_bf16_f32 v157, v168, v169
	v_mul_f32_e32 v166, v165, v58
	v_mul_f32_e32 v167, v165, v59
	v_mul_f32_e32 v168, v165, v60
	v_mul_f32_e32 v169, v165, v61
	v_exp_f32_e32 v166, v166
	v_exp_f32_e32 v167, v167
	v_exp_f32_e32 v168, v168
	v_exp_f32_e32 v169, v169
	v_add_f32_e32 v166, 1.0, v166
	v_add_f32_e32 v167, 1.0, v167
	v_add_f32_e32 v168, 1.0, v168
	v_add_f32_e32 v169, 1.0, v169
	v_rcp_f32_e32 v166, v166
	v_rcp_f32_e32 v167, v167
	v_rcp_f32_e32 v168, v168
	v_rcp_f32_e32 v169, v169
	v_cvt_pk_bf16_f32 v158, v166, v167
	v_cvt_pk_bf16_f32 v159, v168, v169
	v_mul_f32_e32 v166, v165, v62
	v_mul_f32_e32 v167, v165, v63
	v_mul_f32_e32 v168, v165, v64
	v_mul_f32_e32 v169, v165, v65
	v_exp_f32_e32 v166, v166
	v_exp_f32_e32 v167, v167
	v_exp_f32_e32 v168, v168
	v_exp_f32_e32 v169, v169
	v_add_f32_e32 v166, 1.0, v166
	v_add_f32_e32 v167, 1.0, v167
	v_add_f32_e32 v168, 1.0, v168
	v_add_f32_e32 v169, 1.0, v169
	v_rcp_f32_e32 v166, v166
	v_rcp_f32_e32 v167, v167
	v_rcp_f32_e32 v168, v168
	v_rcp_f32_e32 v169, v169
	v_cvt_pk_bf16_f32 v160, v166, v167
	v_cvt_pk_bf16_f32 v161, v168, v169
	s_add_u32 m0, s52, 0x0
	s_nop 0
	global_load_lds_dwordx4 v244, s[28:29]
	global_load_lds_dwordx4 v245, s[28:29] offset:1024
	s_add_u32 m0, s53, 0x0
	s_nop 0
	global_load_lds_dwordx4 v251, s[30:31]
	global_load_lds_dwordx4 v251, s[30:31] offset:1024
	s_add_u32 m0, s52, 0x4000
	s_add_u32 s28, s28, 0x40
	s_addc_u32 s29, s29, 0
	global_load_lds_dwordx4 v244, s[28:29]
	global_load_lds_dwordx4 v245, s[28:29] offset:1024
	s_add_u32 m0, s53, 0x4000
	s_add_u32 s30, s30, 0x10000
	s_addc_u32 s31, s31, 0
	global_load_lds_dwordx4 v251, s[30:31]
	global_load_lds_dwordx4 v251, s[30:31] offset:1024
	s_add_u32 m0, s52, 0x8000
	s_add_u32 s28, s28, 0x40
	s_addc_u32 s29, s29, 0
	global_load_lds_dwordx4 v244, s[28:29]
	global_load_lds_dwordx4 v245, s[28:29] offset:1024
	s_add_u32 m0, s53, 0x8000
	s_add_u32 s30, s30, 0x10000
	s_addc_u32 s31, s31, 0
	global_load_lds_dwordx4 v251, s[30:31]
	global_load_lds_dwordx4 v251, s[30:31] offset:1024
	s_waitcnt vmcnt(8)
	s_barrier
	ds_read_b128 v[208:211], v240 offset:0
	ds_read_b128 v[224:227], v241 offset:0
	ds_read_b128 v[228:231], v241 offset:1024
	ds_read_b128 v[232:235], v241 offset:2048
	ds_read_b128 v[236:239], v241 offset:3072
	s_add_u32 m0, s52, 0xc000
	s_add_u32 s28, s28, 0x40
	s_addc_u32 s29, s29, 0
	global_load_lds_dwordx4 v244, s[28:29]
	global_load_lds_dwordx4 v245, s[28:29] offset:1024
	s_add_u32 m0, s53, 0xc000
	s_add_u32 s30, s30, 0x10000
	s_addc_u32 s31, s31, 0
	global_load_lds_dwordx4 v251, s[30:31]
	global_load_lds_dwordx4 v251, s[30:31] offset:1024
	ds_read_b128 v[212:215], v240 offset:1024
	ds_read_b128 v[216:219], v240 offset:2048
	ds_read_b128 v[220:223], v240 offset:3072
	s_waitcnt lgkmcnt(6)
	v_mfma_f32_16x16x32_bf16 v[2:5], v[224:227], v[208:211], 0
	s_waitcnt lgkmcnt(5)
	v_mfma_f32_16x16x32_bf16 v[6:9], v[228:231], v[208:211], 0
	s_waitcnt lgkmcnt(4)
	v_mfma_f32_16x16x32_bf16 v[10:13], v[232:235], v[208:211], 0
	s_waitcnt lgkmcnt(3)
	v_mfma_f32_16x16x32_bf16 v[14:17], v[236:239], v[208:211], 0
	s_waitcnt lgkmcnt(2)
	v_mfma_f32_16x16x32_bf16 v[18:21], v[224:227], v[212:215], 0
	v_mfma_f32_16x16x32_bf16 v[22:25], v[228:231], v[212:215], 0
	v_mfma_f32_16x16x32_bf16 v[26:29], v[232:235], v[212:215], 0
	v_mfma_f32_16x16x32_bf16 v[30:33], v[236:239], v[212:215], 0
	s_waitcnt lgkmcnt(1)
	v_mfma_f32_16x16x32_bf16 v[34:37], v[224:227], v[216:219], 0
	v_mfma_f32_16x16x32_bf16 v[38:41], v[228:231], v[216:219], 0
	v_mfma_f32_16x16x32_bf16 v[42:45], v[232:235], v[216:219], 0
	v_mfma_f32_16x16x32_bf16 v[46:49], v[236:239], v[216:219], 0
	s_waitcnt lgkmcnt(0)
	v_mfma_f32_16x16x32_bf16 v[50:53], v[224:227], v[220:223], 0
	v_mfma_f32_16x16x32_bf16 v[54:57], v[228:231], v[220:223], 0
	v_mfma_f32_16x16x32_bf16 v[58:61], v[232:235], v[220:223], 0
	v_mfma_f32_16x16x32_bf16 v[62:65], v[236:239], v[220:223], 0
	s_waitcnt vmcnt(8)
	s_barrier
; #define BLOAD(A_, B_, kt) do { _Pragma("unroll") for (int i = 0; i < 4; ++i) { \
;     A_[i] = *(const u32x4*)((const char*)Ap + (aoff + (unsigned)(32 * i * lda + (kt) * 64) * 2u)); B_[i] = *(const u32x4*)((const char*)Wt + (woff + (unsigned)(32 * i * K + (kt) * 64) * 2u)); } } while (0)
; #define BLOAD(A_, B_, kt) do { _Pragma("unroll") for (int i = 0; i < 4; ++i) { \
;     A_[i] = *(const u32x4*)((const char*)Ap + (aoff + (unsigned)(32 * i * lda + (kt) * 64) * 2u)); B_[i] = *(const u32x4*)((const char*)Wt + (woff + (unsigned)(32 * i * K + (kt) * 64) * 2u)); } } while (0)
; #define BSTORE(A_, B_, buf) do { _Pragma("unroll") for (int i = 0; i < 4; ++i) { \
;     *(u32x4*)&As[(buf) * GBUF + (srow + 32 * i) * LDT + sc8] = A_[i]; \
;     *(u32x4*)&Bs[(buf) * GBUF + (srow + 32 * i) * LDT + sc8] = B_[i]; } } while (0)
; template <bool ROWNORM, int NK>
; DI void gemm_main_bf(const u16* __restrict__ Ap, int lda, const u16* __restrict__ Wt, f32x16 (&acc)[2][2], char* smem, float* rinv_s) {
;     ...
;   __builtin_amdgcn_s_setprio(0);
;   BLOAD(a0, b0, 0); BLOAD(a1, b1, 1);
;   __syncthreads();
;   BSTORE(a0, b0, 0);
;   BLOAD(a0, b0, 2);
;   __syncthreads();
; #pragma unroll
;   for (int kt = 0; kt < nk; kt += 2) {
;     BCOMP(0);
;     BSTORE(a1, b1, 1);
;     if (kt + 3 < nk) BLOAD(a1, b1, kt + 3);
;     __syncthreads();
;     BCOMP(1);
;     if (kt + 2 < nk) { BSTORE(a0, b0, 0); if (kt + 4 < nk) BLOAD(a0, b0, kt + 4); }
;     __syncthreads();
	ds_read_b128 v[208:211], v240 offset:16384
	ds_read_b128 v[224:227], v241 offset:16384
	ds_read_b128 v[228:231], v241 offset:17408
	ds_read_b128 v[232:235], v241 offset:18432
	ds_read_b128 v[236:239], v241 offset:19456
	s_add_u32 m0, s52, 0x0
	s_add_u32 s28, s28, 0x40
	s_addc_u32 s29, s29, 0
	global_load_lds_dwordx4 v244, s[28:29]
	global_load_lds_dwordx4 v245, s[28:29] offset:1024
	s_add_u32 m0, s53, 0x0
	s_add_u32 s30, s30, 0x10000
	s_addc_u32 s31, s31, 0
	global_load_lds_dwordx4 v251, s[30:31]
	global_load_lds_dwordx4 v251, s[30:31] offset:1024
	ds_read_b128 v[212:215], v240 offset:17408
	ds_read_b128 v[216:219], v240 offset:18432
	ds_read_b128 v[220:223], v240 offset:19456
	s_waitcnt lgkmcnt(6)
	v_mfma_f32_16x16x32_bf16 v[2:5], v[224:227], v[208:211], v[2:5]
	s_waitcnt lgkmcnt(5)
	v_mfma_f32_16x16x32_bf16 v[6:9], v[228:231], v[208:211], v[6:9]
	s_waitcnt lgkmcnt(4)
	v_mfma_f32_16x16x32_bf16 v[10:13], v[232:235], v[208:211], v[10:13]
	s_waitcnt lgkmcnt(3)
	v_mfma_f32_16x16x32_bf16 v[14:17], v[236:239], v[208:211], v[14:17]
	s_waitcnt lgkmcnt(2)
	v_mfma_f32_16x16x32_bf16 v[18:21], v[224:227], v[212:215], v[18:21]
	v_mfma_f32_16x16x32_bf16 v[22:25], v[228:231], v[212:215], v[22:25]
	v_mfma_f32_16x16x32_bf16 v[26:29], v[232:235], v[212:215], v[26:29]
	v_mfma_f32_16x16x32_bf16 v[30:33], v[236:239], v[212:215], v[30:33]
	s_waitcnt lgkmcnt(1)
	v_mfma_f32_16x16x32_bf16 v[34:37], v[224:227], v[216:219], v[34:37]
	v_mfma_f32_16x16x32_bf16 v[38:41], v[228:231], v[216:219], v[38:41]
	v_mfma_f32_16x16x32_bf16 v[42:45], v[232:235], v[216:219], v[42:45]
	v_mfma_f32_16x16x32_bf16 v[46:49], v[236:239], v[216:219], v[46:49]
	s_waitcnt lgkmcnt(0)
	v_mfma_f32_16x16x32_bf16 v[50:53], v[224:227], v[220:223], v[50:53]
	v_mfma_f32_16x16x32_bf16 v[54:57], v[228:231], v[220:223], v[54:57]
	v_mfma_f32_16x16x32_bf16 v[58:61], v[232:235], v[220:223], v[58:61]
	v_mfma_f32_16x16x32_bf16 v[62:65], v[236:239], v[220:223], v[62:65]
	s_waitcnt vmcnt(8)
	s_barrier
	ds_read_b128 v[208:211], v240 offset:32768
	ds_read_b128 v[224:227], v241 offset:32768
	ds_read_b128 v[228:231], v241 offset:33792
	ds_read_b128 v[232:235], v241 offset:34816
	ds_read_b128 v[236:239], v241 offset:35840
	s_add_u32 m0, s52, 0x4000
	s_add_u32 s28, s28, 0x40
	s_addc_u32 s29, s29, 0
	global_load_lds_dwordx4 v244, s[28:29]
	global_load_lds_dwordx4 v245, s[28:29] offset:1024
	s_add_u32 m0, s53, 0x4000
	s_add_u32 s30, s30, 0x10000
	s_addc_u32 s31, s31, 0
	global_load_lds_dwordx4 v251, s[30:31]
	global_load_lds_dwordx4 v251, s[30:31] offset:1024
	ds_read_b128 v[212:215], v240 offset:33792
	ds_read_b128 v[216:219], v240 offset:34816
	ds_read_b128 v[220:223], v240 offset:35840
	s_waitcnt lgkmcnt(6)
	v_mfma_f32_16x16x32_bf16 v[2:5], v[224:227], v[208:211], v[2:5]
	s_waitcnt lgkmcnt(5)
	v_mfma_f32_16x16x32_bf16 v[6:9], v[228:231], v[208:211], v[6:9]
	s_waitcnt lgkmcnt(4)
	v_mfma_f32_16x16x32_bf16 v[10:13], v[232:235], v[208:211], v[10:13]
	s_waitcnt lgkmcnt(3)
	v_mfma_f32_16x16x32_bf16 v[14:17], v[236:239], v[208:211], v[14:17]
	s_waitcnt lgkmcnt(2)
	v_mfma_f32_16x16x32_bf16 v[18:21], v[224:227], v[212:215], v[18:21]
	v_mfma_f32_16x16x32_bf16 v[22:25], v[228:231], v[212:215], v[22:25]
	v_mfma_f32_16x16x32_bf16 v[26:29], v[232:235], v[212:215], v[26:29]
	v_mfma_f32_16x16x32_bf16 v[30:33], v[236:239], v[212:215], v[30:33]
	s_waitcnt lgkmcnt(1)
	v_mfma_f32_16x16x32_bf16 v[34:37], v[224:227], v[216:219], v[34:37]
	v_mfma_f32_16x16x32_bf16 v[38:41], v[228:231], v[216:219], v[38:41]
	v_mfma_f32_16x16x32_bf16 v[42:45], v[232:235], v[216:219], v[42:45]
	v_mfma_f32_16x16x32_bf16 v[46:49], v[236:239], v[216:219], v[46:49]
	s_waitcnt lgkmcnt(0)
	v_mfma_f32_16x16x32_bf16 v[50:53], v[224:227], v[220:223], v[50:53]
	v_mfma_f32_16x16x32_bf16 v[54:57], v[228:231], v[220:223], v[54:57]
	v_mfma_f32_16x16x32_bf16 v[58:61], v[232:235], v[220:223], v[58:61]
	v_mfma_f32_16x16x32_bf16 v[62:65], v[236:239], v[220:223], v[62:65]
	s_waitcnt vmcnt(8)
	s_barrier
	ds_read_b128 v[208:211], v240 offset:49152
	ds_read_b128 v[224:227], v241 offset:49152
	ds_read_b128 v[228:231], v241 offset:50176
	ds_read_b128 v[232:235], v241 offset:51200
	ds_read_b128 v[236:239], v241 offset:52224
	s_add_u32 m0, s52, 0x8000
	s_add_u32 s28, s28, 0x40
	s_addc_u32 s29, s29, 0
	global_load_lds_dwordx4 v244, s[28:29]
	global_load_lds_dwordx4 v245, s[28:29] offset:1024
	s_add_u32 m0, s53, 0x8000
	s_add_u32 s30, s30, 0x10000
	s_addc_u32 s31, s31, 0
	global_load_lds_dwordx4 v251, s[30:31]
	global_load_lds_dwordx4 v251, s[30:31] offset:1024
	ds_read_b128 v[212:215], v240 offset:50176
	ds_read_b128 v[216:219], v240 offset:51200
	ds_read_b128 v[220:223], v240 offset:52224
	s_waitcnt lgkmcnt(6)
	v_mfma_f32_16x16x32_bf16 v[2:5], v[224:227], v[208:211], v[2:5]
	s_waitcnt lgkmcnt(5)
	v_mfma_f32_16x16x32_bf16 v[6:9], v[228:231], v[208:211], v[6:9]
	s_waitcnt lgkmcnt(4)
	v_mfma_f32_16x16x32_bf16 v[10:13], v[232:235], v[208:211], v[10:13]
	s_waitcnt lgkmcnt(3)
	v_mfma_f32_16x16x32_bf16 v[14:17], v[236:239], v[208:211], v[14:17]
	s_waitcnt lgkmcnt(2)
	v_mfma_f32_16x16x32_bf16 v[18:21], v[224:227], v[212:215], v[18:21]
	v_mfma_f32_16x16x32_bf16 v[22:25], v[228:231], v[212:215], v[22:25]
	v_mfma_f32_16x16x32_bf16 v[26:29], v[232:235], v[212:215], v[26:29]
	v_mfma_f32_16x16x32_bf16 v[30:33], v[236:239], v[212:215], v[30:33]
	s_waitcnt lgkmcnt(1)
	v_mfma_f32_16x16x32_bf16 v[34:37], v[224:227], v[216:219], v[34:37]
	v_mfma_f32_16x16x32_bf16 v[38:41], v[228:231], v[216:219], v[38:41]
	v_mfma_f32_16x16x32_bf16 v[42:45], v[232:235], v[216:219], v[42:45]
	v_mfma_f32_16x16x32_bf16 v[46:49], v[236:239], v[216:219], v[46:49]
	s_waitcnt lgkmcnt(0)
	v_mfma_f32_16x16x32_bf16 v[50:53], v[224:227], v[220:223], v[50:53]
	v_mfma_f32_16x16x32_bf16 v[54:57], v[228:231], v[220:223], v[54:57]
	v_mfma_f32_16x16x32_bf16 v[58:61], v[232:235], v[220:223], v[58:61]
	v_mfma_f32_16x16x32_bf16 v[62:65], v[236:239], v[220:223], v[62:65]
	s_mov_b32 s74, 2

; #define BLOAD(A_, B_, kt) do { _Pragma("unroll") for (int i = 0; i < 4; ++i) { \
;     A_[i] = *(const u32x4*)((const char*)Ap + (aoff + (unsigned)(32 * i * lda + (kt) * 64) * 2u)); B_[i] = *(const u32x4*)((const char*)Wt + (woff + (unsigned)(32 * i * K + (kt) * 64) * 2u)); } } while (0)
; DI RowSS rowss_load(const float* ps, int m0) { const int tid = TID(); const float* q = ps + (size_t)(m0 + (tid >> 1)) * 16 + (tid & 1) * 8; RowSS r; r.a = *(const f32x4*)q; r.b = *(const f32x4*)(q + 4); return r; }
; #define BLOAD(A_, B_, kt) do { _Pragma("unroll") for (int i = 0; i < 4; ++i) { \
;     A_[i] = *(const u32x4*)((const char*)Ap + (aoff + (unsigned)(32 * i * lda + (kt) * 64) * 2u)); B_[i] = *(const u32x4*)((const char*)Wt + (woff + (unsigned)(32 * i * K + (kt) * 64) * 2u)); } } while (0)
; #define BSTORE(A_, B_, buf) do { _Pragma("unroll") for (int i = 0; i < 4; ++i) { \
;     *(u32x4*)&As[(buf) * GBUF + (srow + 32 * i) * LDT + sc8] = A_[i]; \
;     *(u32x4*)&Bs[(buf) * GBUF + (srow + 32 * i) * LDT + sc8] = B_[i]; } } while (0)
; template <int NK>
; DI void gemm_run(PF& pf, const u16* __restrict__ Ap, int lda, const u16* __restrict__ Wt, f32x16 (&acc)[2][2], char* smem) {
;     ...
;   __builtin_amdgcn_s_setprio(0);
;   __syncthreads();
;   BSTORE(pf.a0, pf.b0, 0);
;   BLOAD(pf.a0, pf.b0, 2);
;   __syncthreads();
; #pragma unroll
;   for (int kt = 0; kt < nk; kt += 2) {
;     BCOMP(0);
;     BSTORE(pf.a1, pf.b1, 1);
;     if (kt + 3 < nk) BLOAD(pf.a1, pf.b1, kt + 3);
;     __syncthreads();
;     BCOMP(1);
;     if (kt + 2 < nk) { BSTORE(pf.a0, pf.b0, 0); if (kt + 4 < nk) BLOAD(pf.a0, pf.b0, kt + 4); }
;     __syncthreads();
;   }
; DI void tile_inproj(const Params& p, int l, const Chunk& ck, int tile, int next, PF& pf, char* smem) {
;     ...
;   const int mi = tile & (MTN - 1), nj = tile >> MTS; const int ni = (nj < 45) ? nj : 69; const int m0 = mi * 128;
;   const u16* Ap; const u16* Wt; inproj_ptrs(p, l, tile, Ap, Wt);
;   f32x16 acc[2][2]; zero_acc(acc);
;   const RowSS rss = rowss_load((const float*)(p.ws + OFF_PSIN), m0);
;   gemm_run<16>(pf, Ap, 1024, Wt, acc, smem);
.Linp_nokr:
	s_barrier
	s_mov_b32 s15, 0
	s_cmp_lt_u32 s30, 24
	s_cbranch_scc1 .Linp_dirk
	s_cmp_gt_u32 s30, 35
	s_cbranch_scc1 .Linp_dirk
	s_add_u32 m0, s46, 0x0
	s_nop 0
	global_load_lds_dwordx4 v138, s[48:49]
	global_load_lds_dwordx4 v139, s[48:49] offset:1024
	s_add_u32 m0, s47, 0x0
	s_nop 0
	global_load_lds_dwordx4 v140, s[50:51]
	global_load_lds_dwordx4 v141, s[50:51] offset:1024
	global_load_lds_dwordx4 v142, s[50:51] offset:2048
	global_load_lds_dwordx4 v143, s[50:51] offset:3072
	s_add_u32 m0, s46, 0x6000
	s_add_u32 s48, s48, 0x100000
	s_addc_u32 s49, s49, 0
	global_load_lds_dwordx4 v138, s[48:49]
	global_load_lds_dwordx4 v139, s[48:49] offset:1024
	s_add_u32 m0, s47, 0x6000
	s_add_u32 s50, s50, s13
	s_addc_u32 s51, s51, 0
	global_load_lds_dwordx4 v140, s[50:51]
	global_load_lds_dwordx4 v141, s[50:51] offset:1024
	global_load_lds_dwordx4 v142, s[50:51] offset:2048
	global_load_lds_dwordx4 v143, s[50:51] offset:3072
	s_waitcnt vmcnt(6)
	s_barrier
	ds_read_b128 v[224:227], v126 offset:0
	ds_read_b128 v[240:243], v128 offset:0
	ds_read_b128 v[244:247], v128 offset:1024
	ds_read_b128 v[248:251], v128 offset:2048
	ds_read_b128 v[156:159], v128 offset:3072
	s_add_u32 m0, s46, 0xc000
	s_add_u32 s48, s48, 0x100000
	s_addc_u32 s49, s49, 0
	global_load_lds_dwordx4 v138, s[48:49]
	global_load_lds_dwordx4 v139, s[48:49] offset:1024
	s_add_u32 m0, s47, 0xc000
	s_add_u32 s50, s50, s13
	s_addc_u32 s51, s51, 0
	global_load_lds_dwordx4 v140, s[50:51]
	global_load_lds_dwordx4 v141, s[50:51] offset:1024
	global_load_lds_dwordx4 v142, s[50:51] offset:2048
	global_load_lds_dwordx4 v143, s[50:51] offset:3072
	ds_read_b128 v[228:231], v126 offset:1024
	ds_read_b128 v[232:235], v126 offset:2048
	ds_read_b128 v[236:239], v126 offset:3072
	ds_read_b128 v[160:163], v128 offset:8192
	ds_read_b128 v[164:167], v128 offset:9216
	ds_read_b128 v[168:171], v128 offset:10240
	ds_read_b128 v[122:125], v128 offset:11264
	s_waitcnt lgkmcnt(10)
	v_mfma_f32_16x16x32_bf16 v[2:5], v[224:227], v[240:243], 0
	s_waitcnt lgkmcnt(9)
	v_mfma_f32_16x16x32_bf16 v[6:9], v[224:227], v[244:247], 0
	s_waitcnt lgkmcnt(8)
	v_mfma_f32_16x16x32_bf16 v[10:13], v[224:227], v[248:251], 0
	s_waitcnt lgkmcnt(7)
	v_mfma_f32_16x16x32_bf16 v[14:17], v[224:227], v[156:159], 0
	s_waitcnt lgkmcnt(6)
	v_mfma_f32_16x16x32_bf16 v[18:21], v[228:231], v[240:243], 0
	v_mfma_f32_16x16x32_bf16 v[22:25], v[228:231], v[244:247], 0
	v_mfma_f32_16x16x32_bf16 v[26:29], v[228:231], v[248:251], 0
	v_mfma_f32_16x16x32_bf16 v[30:33], v[228:231], v[156:159], 0
	s_waitcnt lgkmcnt(5)
	v_mfma_f32_16x16x32_bf16 v[34:37], v[232:235], v[240:243], 0
	v_mfma_f32_16x16x32_bf16 v[38:41], v[232:235], v[244:247], 0
	v_mfma_f32_16x16x32_bf16 v[42:45], v[232:235], v[248:251], 0
	v_mfma_f32_16x16x32_bf16 v[46:49], v[232:235], v[156:159], 0
	s_waitcnt lgkmcnt(4)
	v_mfma_f32_16x16x32_bf16 v[50:53], v[236:239], v[240:243], 0
	v_mfma_f32_16x16x32_bf16 v[54:57], v[236:239], v[244:247], 0
	v_mfma_f32_16x16x32_bf16 v[58:61], v[236:239], v[248:251], 0
	v_mfma_f32_16x16x32_bf16 v[62:65], v[236:239], v[156:159], 0
	s_waitcnt lgkmcnt(3)
	v_mfma_f32_16x16x32_bf16 v[74:77], v[224:227], v[160:163], 0
	s_waitcnt lgkmcnt(2)
	v_mfma_f32_16x16x32_bf16 v[78:81], v[224:227], v[164:167], 0
	s_waitcnt lgkmcnt(1)
	v_mfma_f32_16x16x32_bf16 v[82:85], v[224:227], v[168:171], 0
	s_waitcnt lgkmcnt(0)
	v_mfma_f32_16x16x32_bf16 v[86:89], v[224:227], v[122:125], 0
	v_mfma_f32_16x16x32_bf16 v[90:93], v[228:231], v[160:163], 0
	v_mfma_f32_16x16x32_bf16 v[94:97], v[228:231], v[164:167], 0
	v_mfma_f32_16x16x32_bf16 v[98:101], v[228:231], v[168:171], 0
	v_mfma_f32_16x16x32_bf16 v[102:105], v[228:231], v[122:125], 0
	v_mfma_f32_16x16x32_bf16 v[106:109], v[232:235], v[160:163], 0
	v_mfma_f32_16x16x32_bf16 v[110:113], v[232:235], v[164:167], 0
	v_mfma_f32_16x16x32_bf16 v[114:117], v[232:235], v[168:171], 0
	v_mfma_f32_16x16x32_bf16 v[118:121], v[232:235], v[122:125], 0
	v_mfma_f32_16x16x32_bf16 v[208:211], v[236:239], v[160:163], 0
	v_mfma_f32_16x16x32_bf16 v[212:215], v[236:239], v[164:167], 0
	v_mfma_f32_16x16x32_bf16 v[216:219], v[236:239], v[168:171], 0
	v_mfma_f32_16x16x32_bf16 v[220:223], v[236:239], v[122:125], 0
	s_waitcnt vmcnt(6)
	s_barrier
; #define BLOAD(A_, B_, kt) do { _Pragma("unroll") for (int i = 0; i < 4; ++i) { \
;     A_[i] = *(const u32x4*)((const char*)Ap + (aoff + (unsigned)(32 * i * lda + (kt) * 64) * 2u)); B_[i] = *(const u32x4*)((const char*)Wt + (woff + (unsigned)(32 * i * K + (kt) * 64) * 2u)); } } while (0)
; #define BLOAD(A_, B_, kt) do { _Pragma("unroll") for (int i = 0; i < 4; ++i) { \
;     A_[i] = *(const u32x4*)((const char*)Ap + (aoff + (unsigned)(32 * i * lda + (kt) * 64) * 2u)); B_[i] = *(const u32x4*)((const char*)Wt + (woff + (unsigned)(32 * i * K + (kt) * 64) * 2u)); } } while (0)
; #define BSTORE(A_, B_, buf) do { _Pragma("unroll") for (int i = 0; i < 4; ++i) { \
;     *(u32x4*)&As[(buf) * GBUF + (srow + 32 * i) * LDT + sc8] = A_[i]; \
;     *(u32x4*)&Bs[(buf) * GBUF + (srow + 32 * i) * LDT + sc8] = B_[i]; } } while (0)
; template <int NK>
; DI void gemm_run(PF& pf, const u16* __restrict__ Ap, int lda, const u16* __restrict__ Wt, f32x16 (&acc)[2][2], char* smem) {
;     ...
;   __builtin_amdgcn_s_setprio(0);
;   __syncthreads();
;   BSTORE(pf.a0, pf.b0, 0);
;   BLOAD(pf.a0, pf.b0, 2);
;   __syncthreads();
; #pragma unroll
;   for (int kt = 0; kt < nk; kt += 2) {
;     BCOMP(0);
;     BSTORE(pf.a1, pf.b1, 1);
;     if (kt + 3 < nk) BLOAD(pf.a1, pf.b1, kt + 3);
;     __syncthreads();
;     BCOMP(1);
;     if (kt + 2 < nk) { BSTORE(pf.a0, pf.b0, 0); if (kt + 4 < nk) BLOAD(pf.a0, pf.b0, kt + 4); }
;     __syncthreads();
;   }
	ds_read_b128 v[224:227], v126 offset:24576
	ds_read_b128 v[240:243], v128 offset:24576
	ds_read_b128 v[244:247], v128 offset:25600
	ds_read_b128 v[248:251], v128 offset:26624
	ds_read_b128 v[156:159], v128 offset:27648
	s_add_u32 m0, s46, 0x0
	s_add_u32 s48, s48, 0x100000
	s_addc_u32 s49, s49, 0
	global_load_lds_dwordx4 v138, s[48:49]
	global_load_lds_dwordx4 v139, s[48:49] offset:1024
	s_add_u32 m0, s47, 0x0
	s_add_u32 s50, s50, s13
	s_addc_u32 s51, s51, 0
	global_load_lds_dwordx4 v140, s[50:51]
	global_load_lds_dwordx4 v141, s[50:51] offset:1024
	global_load_lds_dwordx4 v142, s[50:51] offset:2048
	global_load_lds_dwordx4 v143, s[50:51] offset:3072
	ds_read_b128 v[228:231], v126 offset:25600
	ds_read_b128 v[232:235], v126 offset:26624
	ds_read_b128 v[236:239], v126 offset:27648
	ds_read_b128 v[160:163], v128 offset:32768
	ds_read_b128 v[164:167], v128 offset:33792
	ds_read_b128 v[168:171], v128 offset:34816
	ds_read_b128 v[122:125], v128 offset:35840
	s_waitcnt lgkmcnt(10)
	v_mfma_f32_16x16x32_bf16 v[2:5], v[224:227], v[240:243], v[2:5]
	s_waitcnt lgkmcnt(9)
	v_mfma_f32_16x16x32_bf16 v[6:9], v[224:227], v[244:247], v[6:9]
	s_waitcnt lgkmcnt(8)
	v_mfma_f32_16x16x32_bf16 v[10:13], v[224:227], v[248:251], v[10:13]
	s_waitcnt lgkmcnt(7)
	v_mfma_f32_16x16x32_bf16 v[14:17], v[224:227], v[156:159], v[14:17]
	s_waitcnt lgkmcnt(6)
	v_mfma_f32_16x16x32_bf16 v[18:21], v[228:231], v[240:243], v[18:21]
	v_mfma_f32_16x16x32_bf16 v[22:25], v[228:231], v[244:247], v[22:25]
	v_mfma_f32_16x16x32_bf16 v[26:29], v[228:231], v[248:251], v[26:29]
	v_mfma_f32_16x16x32_bf16 v[30:33], v[228:231], v[156:159], v[30:33]
	s_waitcnt lgkmcnt(5)
	v_mfma_f32_16x16x32_bf16 v[34:37], v[232:235], v[240:243], v[34:37]
	v_mfma_f32_16x16x32_bf16 v[38:41], v[232:235], v[244:247], v[38:41]
	v_mfma_f32_16x16x32_bf16 v[42:45], v[232:235], v[248:251], v[42:45]
	v_mfma_f32_16x16x32_bf16 v[46:49], v[232:235], v[156:159], v[46:49]
	s_waitcnt lgkmcnt(4)
	v_mfma_f32_16x16x32_bf16 v[50:53], v[236:239], v[240:243], v[50:53]
	v_mfma_f32_16x16x32_bf16 v[54:57], v[236:239], v[244:247], v[54:57]
	v_mfma_f32_16x16x32_bf16 v[58:61], v[236:239], v[248:251], v[58:61]
	v_mfma_f32_16x16x32_bf16 v[62:65], v[236:239], v[156:159], v[62:65]
	s_waitcnt lgkmcnt(3)
	v_mfma_f32_16x16x32_bf16 v[74:77], v[224:227], v[160:163], v[74:77]
	s_waitcnt lgkmcnt(2)
	v_mfma_f32_16x16x32_bf16 v[78:81], v[224:227], v[164:167], v[78:81]
	s_waitcnt lgkmcnt(1)
	v_mfma_f32_16x16x32_bf16 v[82:85], v[224:227], v[168:171], v[82:85]
	s_waitcnt lgkmcnt(0)
	v_mfma_f32_16x16x32_bf16 v[86:89], v[224:227], v[122:125], v[86:89]
	v_mfma_f32_16x16x32_bf16 v[90:93], v[228:231], v[160:163], v[90:93]
	v_mfma_f32_16x16x32_bf16 v[94:97], v[228:231], v[164:167], v[94:97]
	v_mfma_f32_16x16x32_bf16 v[98:101], v[228:231], v[168:171], v[98:101]
	v_mfma_f32_16x16x32_bf16 v[102:105], v[228:231], v[122:125], v[102:105]
	v_mfma_f32_16x16x32_bf16 v[106:109], v[232:235], v[160:163], v[106:109]
	v_mfma_f32_16x16x32_bf16 v[110:113], v[232:235], v[164:167], v[110:113]
	v_mfma_f32_16x16x32_bf16 v[114:117], v[232:235], v[168:171], v[114:117]
	v_mfma_f32_16x16x32_bf16 v[118:121], v[232:235], v[122:125], v[118:121]
	v_mfma_f32_16x16x32_bf16 v[208:211], v[236:239], v[160:163], v[208:211]
	v_mfma_f32_16x16x32_bf16 v[212:215], v[236:239], v[164:167], v[212:215]
	v_mfma_f32_16x16x32_bf16 v[216:219], v[236:239], v[168:171], v[216:219]
	v_mfma_f32_16x16x32_bf16 v[220:223], v[236:239], v[122:125], v[220:223]
	s_waitcnt vmcnt(6)
	s_barrier
	ds_read_b128 v[224:227], v126 offset:49152
	ds_read_b128 v[240:243], v128 offset:49152
	ds_read_b128 v[244:247], v128 offset:50176
	ds_read_b128 v[248:251], v128 offset:51200
	ds_read_b128 v[156:159], v128 offset:52224
	s_add_u32 m0, s46, 0x6000
	s_add_u32 s48, s48, 0x100000
	s_addc_u32 s49, s49, 0
	global_load_lds_dwordx4 v138, s[48:49]
	global_load_lds_dwordx4 v139, s[48:49] offset:1024
	s_add_u32 m0, s47, 0x6000
	s_add_u32 s50, s50, s13
	s_addc_u32 s51, s51, 0
	global_load_lds_dwordx4 v140, s[50:51]
	global_load_lds_dwordx4 v141, s[50:51] offset:1024
	global_load_lds_dwordx4 v142, s[50:51] offset:2048
	global_load_lds_dwordx4 v143, s[50:51] offset:3072
	ds_read_b128 v[228:231], v126 offset:50176
	ds_read_b128 v[232:235], v126 offset:51200
	ds_read_b128 v[236:239], v126 offset:52224
	ds_read_b128 v[160:163], v128 offset:57344
	ds_read_b128 v[164:167], v128 offset:58368
	ds_read_b128 v[168:171], v128 offset:59392
	ds_read_b128 v[122:125], v128 offset:60416
	s_waitcnt lgkmcnt(10)
	v_mfma_f32_16x16x32_bf16 v[2:5], v[224:227], v[240:243], v[2:5]
	s_waitcnt lgkmcnt(9)
	v_mfma_f32_16x16x32_bf16 v[6:9], v[224:227], v[244:247], v[6:9]
	s_waitcnt lgkmcnt(8)
	v_mfma_f32_16x16x32_bf16 v[10:13], v[224:227], v[248:251], v[10:13]
	s_waitcnt lgkmcnt(7)
	v_mfma_f32_16x16x32_bf16 v[14:17], v[224:227], v[156:159], v[14:17]
	s_waitcnt lgkmcnt(6)
	v_mfma_f32_16x16x32_bf16 v[18:21], v[228:231], v[240:243], v[18:21]
	v_mfma_f32_16x16x32_bf16 v[22:25], v[228:231], v[244:247], v[22:25]
	v_mfma_f32_16x16x32_bf16 v[26:29], v[228:231], v[248:251], v[26:29]
	v_mfma_f32_16x16x32_bf16 v[30:33], v[228:231], v[156:159], v[30:33]
	s_waitcnt lgkmcnt(5)
	v_mfma_f32_16x16x32_bf16 v[34:37], v[232:235], v[240:243], v[34:37]
	v_mfma_f32_16x16x32_bf16 v[38:41], v[232:235], v[244:247], v[38:41]
	v_mfma_f32_16x16x32_bf16 v[42:45], v[232:235], v[248:251], v[42:45]
	v_mfma_f32_16x16x32_bf16 v[46:49], v[232:235], v[156:159], v[46:49]
	s_waitcnt lgkmcnt(4)
	v_mfma_f32_16x16x32_bf16 v[50:53], v[236:239], v[240:243], v[50:53]
	v_mfma_f32_16x16x32_bf16 v[54:57], v[236:239], v[244:247], v[54:57]
	v_mfma_f32_16x16x32_bf16 v[58:61], v[236:239], v[248:251], v[58:61]
	v_mfma_f32_16x16x32_bf16 v[62:65], v[236:239], v[156:159], v[62:65]
	s_waitcnt lgkmcnt(3)
	v_mfma_f32_16x16x32_bf16 v[74:77], v[224:227], v[160:163], v[74:77]
	s_waitcnt lgkmcnt(2)
	v_mfma_f32_16x16x32_bf16 v[78:81], v[224:227], v[164:167], v[78:81]
	s_waitcnt lgkmcnt(1)
	v_mfma_f32_16x16x32_bf16 v[82:85], v[224:227], v[168:171], v[82:85]
	s_waitcnt lgkmcnt(0)
	v_mfma_f32_16x16x32_bf16 v[86:89], v[224:227], v[122:125], v[86:89]
	v_mfma_f32_16x16x32_bf16 v[90:93], v[228:231], v[160:163], v[90:93]
	v_mfma_f32_16x16x32_bf16 v[94:97], v[228:231], v[164:167], v[94:97]
	v_mfma_f32_16x16x32_bf16 v[98:101], v[228:231], v[168:171], v[98:101]
	v_mfma_f32_16x16x32_bf16 v[102:105], v[228:231], v[122:125], v[102:105]
	v_mfma_f32_16x16x32_bf16 v[106:109], v[232:235], v[160:163], v[106:109]
	v_mfma_f32_16x16x32_bf16 v[110:113], v[232:235], v[164:167], v[110:113]
	v_mfma_f32_16x16x32_bf16 v[114:117], v[232:235], v[168:171], v[114:117]
	v_mfma_f32_16x16x32_bf16 v[118:121], v[232:235], v[122:125], v[118:121]
	v_mfma_f32_16x16x32_bf16 v[208:211], v[236:239], v[160:163], v[208:211]
	v_mfma_f32_16x16x32_bf16 v[212:215], v[236:239], v[164:167], v[212:215]
	v_mfma_f32_16x16x32_bf16 v[216:219], v[236:239], v[168:171], v[216:219]
	v_mfma_f32_16x16x32_bf16 v[220:223], v[236:239], v[122:125], v[220:223]
	s_mov_b32 s12, 9

; #define BLOAD(A_, B_, kt) do { _Pragma("unroll") for (int i = 0; i < 4; ++i) { \
;     A_[i] = *(const u32x4*)((const char*)Ap + (aoff + (unsigned)(32 * i * lda + (kt) * 64) * 2u)); B_[i] = *(const u32x4*)((const char*)Wt + (woff + (unsigned)(32 * i * K + (kt) * 64) * 2u)); } } while (0)
; #define BLOAD(A_, B_, kt) do { _Pragma("unroll") for (int i = 0; i < 4; ++i) { \
;     A_[i] = *(const u32x4*)((const char*)Ap + (aoff + (unsigned)(32 * i * lda + (kt) * 64) * 2u)); B_[i] = *(const u32x4*)((const char*)Wt + (woff + (unsigned)(32 * i * K + (kt) * 64) * 2u)); } } while (0)
; #define BSTORE(A_, B_, buf) do { _Pragma("unroll") for (int i = 0; i < 4; ++i) { \
;     *(u32x4*)&As[(buf) * GBUF + (srow + 32 * i) * LDT + sc8] = A_[i]; \
;     *(u32x4*)&Bs[(buf) * GBUF + (srow + 32 * i) * LDT + sc8] = B_[i]; } } while (0)
; template <int NK>
; DI void gemm_run(PF& pf, const u16* __restrict__ Ap, int lda, const u16* __restrict__ Wt, f32x16 (&acc)[2][2], char* smem) {
;     ...
;   __builtin_amdgcn_s_setprio(0);
;   __syncthreads();
;   BSTORE(pf.a0, pf.b0, 0);
;   BLOAD(pf.a0, pf.b0, 2);
;   __syncthreads();
; #pragma unroll
;   for (int kt = 0; kt < nk; kt += 2) {
;     BCOMP(0);
;     BSTORE(pf.a1, pf.b1, 1);
;     if (kt + 3 < nk) BLOAD(pf.a1, pf.b1, kt + 3);
;     __syncthreads();
;     BCOMP(1);
;     if (kt + 2 < nk) { BSTORE(pf.a0, pf.b0, 0); if (kt + 4 < nk) BLOAD(pf.a0, pf.b0, kt + 4); }
;     __syncthreads();
;   }
.Linp_dirk:
	s_mov_b32 s15, 1
	s_add_u32 m0, s46, 0x0
	s_nop 0
	global_load_lds_dwordx4 v138, s[48:49]
	global_load_lds_dwordx4 v139, s[48:49] offset:1024
	s_add_u32 m0, s47, 0x0
	s_nop 0
	global_load_lds_dwordx4 v140, s[50:51]
	global_load_lds_dwordx4 v141, s[50:51] offset:1024
	global_load_lds_dwordx4 v142, s[50:51] offset:2048
	global_load_lds_dwordx4 v143, s[50:51] offset:3072
	s_add_u32 m0, s46, 0x6000
	s_add_u32 s48, s48, 0x100000
	s_addc_u32 s49, s49, 0
	global_load_lds_dwordx4 v138, s[48:49]
	global_load_lds_dwordx4 v139, s[48:49] offset:1024
	s_add_u32 m0, s47, 0x6000
	s_add_u32 s50, s50, s13
	s_addc_u32 s51, s51, 0
	global_load_lds_dwordx4 v140, s[50:51]
	global_load_lds_dwordx4 v141, s[50:51] offset:1024
	global_load_lds_dwordx4 v142, s[50:51] offset:2048
	global_load_lds_dwordx4 v143, s[50:51] offset:3072
	s_waitcnt vmcnt(6)
	s_barrier
	ds_read_b128 v[224:227], v126 offset:0
	ds_read_b128 v[240:243], v128 offset:0
	ds_read_b128 v[244:247], v128 offset:1024
	ds_read_b128 v[248:251], v128 offset:2048
	ds_read_b128 v[156:159], v128 offset:3072
	s_add_u32 m0, s46, 0xc000
	s_add_u32 s48, s48, 0x100000
	s_addc_u32 s49, s49, 0
	global_load_lds_dwordx4 v138, s[48:49]
	global_load_lds_dwordx4 v139, s[48:49] offset:1024
	s_add_u32 m0, s47, 0xc000
	s_add_u32 s50, s50, s13
	s_addc_u32 s51, s51, 0
	global_load_lds_dwordx4 v140, s[50:51]
	global_load_lds_dwordx4 v141, s[50:51] offset:1024
	global_load_lds_dwordx4 v142, s[50:51] offset:2048
	global_load_lds_dwordx4 v143, s[50:51] offset:3072
	ds_read_b128 v[228:231], v126 offset:1024
	ds_read_b128 v[232:235], v126 offset:2048
	ds_read_b128 v[236:239], v126 offset:3072
	ds_read_b128 v[160:163], v128 offset:8192
	ds_read_b128 v[164:167], v128 offset:9216
	ds_read_b128 v[168:171], v128 offset:10240
	ds_read_b128 v[122:125], v128 offset:11264
	s_waitcnt lgkmcnt(10)
	v_mfma_f32_16x16x32_bf16 v[2:5], v[240:243], v[224:227], 0
	s_waitcnt lgkmcnt(9)
	v_mfma_f32_16x16x32_bf16 v[6:9], v[244:247], v[224:227], 0
	s_waitcnt lgkmcnt(8)
	v_mfma_f32_16x16x32_bf16 v[10:13], v[248:251], v[224:227], 0
	s_waitcnt lgkmcnt(7)
	v_mfma_f32_16x16x32_bf16 v[14:17], v[156:159], v[224:227], 0
	s_waitcnt lgkmcnt(6)
	v_mfma_f32_16x16x32_bf16 v[18:21], v[240:243], v[228:231], 0
	v_mfma_f32_16x16x32_bf16 v[22:25], v[244:247], v[228:231], 0
	v_mfma_f32_16x16x32_bf16 v[26:29], v[248:251], v[228:231], 0
	v_mfma_f32_16x16x32_bf16 v[30:33], v[156:159], v[228:231], 0
	s_waitcnt lgkmcnt(5)
	v_mfma_f32_16x16x32_bf16 v[34:37], v[240:243], v[232:235], 0
	v_mfma_f32_16x16x32_bf16 v[38:41], v[244:247], v[232:235], 0
	v_mfma_f32_16x16x32_bf16 v[42:45], v[248:251], v[232:235], 0
	v_mfma_f32_16x16x32_bf16 v[46:49], v[156:159], v[232:235], 0
	s_waitcnt lgkmcnt(4)
	v_mfma_f32_16x16x32_bf16 v[50:53], v[240:243], v[236:239], 0
	v_mfma_f32_16x16x32_bf16 v[54:57], v[244:247], v[236:239], 0
	v_mfma_f32_16x16x32_bf16 v[58:61], v[248:251], v[236:239], 0
	v_mfma_f32_16x16x32_bf16 v[62:65], v[156:159], v[236:239], 0
	s_waitcnt lgkmcnt(3)
	v_mfma_f32_16x16x32_bf16 v[74:77], v[160:163], v[224:227], 0
	s_waitcnt lgkmcnt(2)
	v_mfma_f32_16x16x32_bf16 v[78:81], v[164:167], v[224:227], 0
	s_waitcnt lgkmcnt(1)
	v_mfma_f32_16x16x32_bf16 v[82:85], v[168:171], v[224:227], 0
	s_waitcnt lgkmcnt(0)
	v_mfma_f32_16x16x32_bf16 v[86:89], v[122:125], v[224:227], 0
	v_mfma_f32_16x16x32_bf16 v[90:93], v[160:163], v[228:231], 0
	v_mfma_f32_16x16x32_bf16 v[94:97], v[164:167], v[228:231], 0
	v_mfma_f32_16x16x32_bf16 v[98:101], v[168:171], v[228:231], 0
	v_mfma_f32_16x16x32_bf16 v[102:105], v[122:125], v[228:231], 0
	v_mfma_f32_16x16x32_bf16 v[106:109], v[160:163], v[232:235], 0
	v_mfma_f32_16x16x32_bf16 v[110:113], v[164:167], v[232:235], 0
	v_mfma_f32_16x16x32_bf16 v[114:117], v[168:171], v[232:235], 0
	v_mfma_f32_16x16x32_bf16 v[118:121], v[122:125], v[232:235], 0
	v_mfma_f32_16x16x32_bf16 v[208:211], v[160:163], v[236:239], 0
	v_mfma_f32_16x16x32_bf16 v[212:215], v[164:167], v[236:239], 0
	v_mfma_f32_16x16x32_bf16 v[216:219], v[168:171], v[236:239], 0
	v_mfma_f32_16x16x32_bf16 v[220:223], v[122:125], v[236:239], 0
	s_waitcnt vmcnt(6)
	s_barrier
; #define BLOAD(A_, B_, kt) do { _Pragma("unroll") for (int i = 0; i < 4; ++i) { \
;     A_[i] = *(const u32x4*)((const char*)Ap + (aoff + (unsigned)(32 * i * lda + (kt) * 64) * 2u)); B_[i] = *(const u32x4*)((const char*)Wt + (woff + (unsigned)(32 * i * K + (kt) * 64) * 2u)); } } while (0)
; #define BLOAD(A_, B_, kt) do { _Pragma("unroll") for (int i = 0; i < 4; ++i) { \
;     A_[i] = *(const u32x4*)((const char*)Ap + (aoff + (unsigned)(32 * i * lda + (kt) * 64) * 2u)); B_[i] = *(const u32x4*)((const char*)Wt + (woff + (unsigned)(32 * i * K + (kt) * 64) * 2u)); } } while (0)
; #define BSTORE(A_, B_, buf) do { _Pragma("unroll") for (int i = 0; i < 4; ++i) { \
;     *(u32x4*)&As[(buf) * GBUF + (srow + 32 * i) * LDT + sc8] = A_[i]; \
;     *(u32x4*)&Bs[(buf) * GBUF + (srow + 32 * i) * LDT + sc8] = B_[i]; } } while (0)
; template <int NK>
; DI void gemm_run(PF& pf, const u16* __restrict__ Ap, int lda, const u16* __restrict__ Wt, f32x16 (&acc)[2][2], char* smem) {
;     ...
;   __builtin_amdgcn_s_setprio(0);
;   __syncthreads();
;   BSTORE(pf.a0, pf.b0, 0);
;   BLOAD(pf.a0, pf.b0, 2);
;   __syncthreads();
; #pragma unroll
;   for (int kt = 0; kt < nk; kt += 2) {
;     BCOMP(0);
;     BSTORE(pf.a1, pf.b1, 1);
;     if (kt + 3 < nk) BLOAD(pf.a1, pf.b1, kt + 3);
;     __syncthreads();
;     BCOMP(1);
;     if (kt + 2 < nk) { BSTORE(pf.a0, pf.b0, 0); if (kt + 4 < nk) BLOAD(pf.a0, pf.b0, kt + 4); }
;     __syncthreads();
;   }
	ds_read_b128 v[224:227], v126 offset:24576
	ds_read_b128 v[240:243], v128 offset:24576
	ds_read_b128 v[244:247], v128 offset:25600
	ds_read_b128 v[248:251], v128 offset:26624
	ds_read_b128 v[156:159], v128 offset:27648
	s_add_u32 m0, s46, 0x0
	s_add_u32 s48, s48, 0x100000
	s_addc_u32 s49, s49, 0
	global_load_lds_dwordx4 v138, s[48:49]
	global_load_lds_dwordx4 v139, s[48:49] offset:1024
	s_add_u32 m0, s47, 0x0
	s_add_u32 s50, s50, s13
	s_addc_u32 s51, s51, 0
	global_load_lds_dwordx4 v140, s[50:51]
	global_load_lds_dwordx4 v141, s[50:51] offset:1024
	global_load_lds_dwordx4 v142, s[50:51] offset:2048
	global_load_lds_dwordx4 v143, s[50:51] offset:3072
	ds_read_b128 v[228:231], v126 offset:25600
	ds_read_b128 v[232:235], v126 offset:26624
	ds_read_b128 v[236:239], v126 offset:27648
	ds_read_b128 v[160:163], v128 offset:32768
	ds_read_b128 v[164:167], v128 offset:33792
	ds_read_b128 v[168:171], v128 offset:34816
	ds_read_b128 v[122:125], v128 offset:35840
	s_waitcnt lgkmcnt(10)
	v_mfma_f32_16x16x32_bf16 v[2:5], v[240:243], v[224:227], v[2:5]
	s_waitcnt lgkmcnt(9)
	v_mfma_f32_16x16x32_bf16 v[6:9], v[244:247], v[224:227], v[6:9]
	s_waitcnt lgkmcnt(8)
	v_mfma_f32_16x16x32_bf16 v[10:13], v[248:251], v[224:227], v[10:13]
	s_waitcnt lgkmcnt(7)
	v_mfma_f32_16x16x32_bf16 v[14:17], v[156:159], v[224:227], v[14:17]
	s_waitcnt lgkmcnt(6)
	v_mfma_f32_16x16x32_bf16 v[18:21], v[240:243], v[228:231], v[18:21]
	v_mfma_f32_16x16x32_bf16 v[22:25], v[244:247], v[228:231], v[22:25]
	v_mfma_f32_16x16x32_bf16 v[26:29], v[248:251], v[228:231], v[26:29]
	v_mfma_f32_16x16x32_bf16 v[30:33], v[156:159], v[228:231], v[30:33]
	s_waitcnt lgkmcnt(5)
	v_mfma_f32_16x16x32_bf16 v[34:37], v[240:243], v[232:235], v[34:37]
	v_mfma_f32_16x16x32_bf16 v[38:41], v[244:247], v[232:235], v[38:41]
	v_mfma_f32_16x16x32_bf16 v[42:45], v[248:251], v[232:235], v[42:45]
	v_mfma_f32_16x16x32_bf16 v[46:49], v[156:159], v[232:235], v[46:49]
	s_waitcnt lgkmcnt(4)
	v_mfma_f32_16x16x32_bf16 v[50:53], v[240:243], v[236:239], v[50:53]
	v_mfma_f32_16x16x32_bf16 v[54:57], v[244:247], v[236:239], v[54:57]
	v_mfma_f32_16x16x32_bf16 v[58:61], v[248:251], v[236:239], v[58:61]
	v_mfma_f32_16x16x32_bf16 v[62:65], v[156:159], v[236:239], v[62:65]
	s_waitcnt lgkmcnt(3)
	v_mfma_f32_16x16x32_bf16 v[74:77], v[160:163], v[224:227], v[74:77]
	s_waitcnt lgkmcnt(2)
	v_mfma_f32_16x16x32_bf16 v[78:81], v[164:167], v[224:227], v[78:81]
	s_waitcnt lgkmcnt(1)
	v_mfma_f32_16x16x32_bf16 v[82:85], v[168:171], v[224:227], v[82:85]
	s_waitcnt lgkmcnt(0)
	v_mfma_f32_16x16x32_bf16 v[86:89], v[122:125], v[224:227], v[86:89]
	v_mfma_f32_16x16x32_bf16 v[90:93], v[160:163], v[228:231], v[90:93]
	v_mfma_f32_16x16x32_bf16 v[94:97], v[164:167], v[228:231], v[94:97]
	v_mfma_f32_16x16x32_bf16 v[98:101], v[168:171], v[228:231], v[98:101]
	v_mfma_f32_16x16x32_bf16 v[102:105], v[122:125], v[228:231], v[102:105]
	v_mfma_f32_16x16x32_bf16 v[106:109], v[160:163], v[232:235], v[106:109]
	v_mfma_f32_16x16x32_bf16 v[110:113], v[164:167], v[232:235], v[110:113]
	v_mfma_f32_16x16x32_bf16 v[114:117], v[168:171], v[232:235], v[114:117]
	v_mfma_f32_16x16x32_bf16 v[118:121], v[122:125], v[232:235], v[118:121]
	v_mfma_f32_16x16x32_bf16 v[208:211], v[160:163], v[236:239], v[208:211]
	v_mfma_f32_16x16x32_bf16 v[212:215], v[164:167], v[236:239], v[212:215]
	v_mfma_f32_16x16x32_bf16 v[216:219], v[168:171], v[236:239], v[216:219]
	v_mfma_f32_16x16x32_bf16 v[220:223], v[122:125], v[236:239], v[220:223]
	s_waitcnt vmcnt(6)
	s_barrier
	ds_read_b128 v[224:227], v126 offset:49152
	ds_read_b128 v[240:243], v128 offset:49152
	ds_read_b128 v[244:247], v128 offset:50176
	ds_read_b128 v[248:251], v128 offset:51200
	ds_read_b128 v[156:159], v128 offset:52224
	s_add_u32 m0, s46, 0x6000
	s_add_u32 s48, s48, 0x100000
	s_addc_u32 s49, s49, 0
	global_load_lds_dwordx4 v138, s[48:49]
	global_load_lds_dwordx4 v139, s[48:49] offset:1024
	s_add_u32 m0, s47, 0x6000
	s_add_u32 s50, s50, s13
	s_addc_u32 s51, s51, 0
	global_load_lds_dwordx4 v140, s[50:51]
	global_load_lds_dwordx4 v141, s[50:51] offset:1024
	global_load_lds_dwordx4 v142, s[50:51] offset:2048
	global_load_lds_dwordx4 v143, s[50:51] offset:3072
	ds_read_b128 v[228:231], v126 offset:50176
	ds_read_b128 v[232:235], v126 offset:51200
	ds_read_b128 v[236:239], v126 offset:52224
	ds_read_b128 v[160:163], v128 offset:57344
	ds_read_b128 v[164:167], v128 offset:58368
	ds_read_b128 v[168:171], v128 offset:59392
	ds_read_b128 v[122:125], v128 offset:60416
	s_waitcnt lgkmcnt(10)
	v_mfma_f32_16x16x32_bf16 v[2:5], v[240:243], v[224:227], v[2:5]
	s_waitcnt lgkmcnt(9)
	v_mfma_f32_16x16x32_bf16 v[6:9], v[244:247], v[224:227], v[6:9]
	s_waitcnt lgkmcnt(8)
	v_mfma_f32_16x16x32_bf16 v[10:13], v[248:251], v[224:227], v[10:13]
	s_waitcnt lgkmcnt(7)
	v_mfma_f32_16x16x32_bf16 v[14:17], v[156:159], v[224:227], v[14:17]
	s_waitcnt lgkmcnt(6)
	v_mfma_f32_16x16x32_bf16 v[18:21], v[240:243], v[228:231], v[18:21]
	v_mfma_f32_16x16x32_bf16 v[22:25], v[244:247], v[228:231], v[22:25]
	v_mfma_f32_16x16x32_bf16 v[26:29], v[248:251], v[228:231], v[26:29]
	v_mfma_f32_16x16x32_bf16 v[30:33], v[156:159], v[228:231], v[30:33]
	s_waitcnt lgkmcnt(5)
	v_mfma_f32_16x16x32_bf16 v[34:37], v[240:243], v[232:235], v[34:37]
	v_mfma_f32_16x16x32_bf16 v[38:41], v[244:247], v[232:235], v[38:41]
	v_mfma_f32_16x16x32_bf16 v[42:45], v[248:251], v[232:235], v[42:45]
	v_mfma_f32_16x16x32_bf16 v[46:49], v[156:159], v[232:235], v[46:49]
	s_waitcnt lgkmcnt(4)
	v_mfma_f32_16x16x32_bf16 v[50:53], v[240:243], v[236:239], v[50:53]
	v_mfma_f32_16x16x32_bf16 v[54:57], v[244:247], v[236:239], v[54:57]
	v_mfma_f32_16x16x32_bf16 v[58:61], v[248:251], v[236:239], v[58:61]
	v_mfma_f32_16x16x32_bf16 v[62:65], v[156:159], v[236:239], v[62:65]
	s_waitcnt lgkmcnt(3)
	v_mfma_f32_16x16x32_bf16 v[74:77], v[160:163], v[224:227], v[74:77]
	s_waitcnt lgkmcnt(2)
	v_mfma_f32_16x16x32_bf16 v[78:81], v[164:167], v[224:227], v[78:81]
	s_waitcnt lgkmcnt(1)
	v_mfma_f32_16x16x32_bf16 v[82:85], v[168:171], v[224:227], v[82:85]
	s_waitcnt lgkmcnt(0)
	v_mfma_f32_16x16x32_bf16 v[86:89], v[122:125], v[224:227], v[86:89]
	v_mfma_f32_16x16x32_bf16 v[90:93], v[160:163], v[228:231], v[90:93]
	v_mfma_f32_16x16x32_bf16 v[94:97], v[164:167], v[228:231], v[94:97]
	v_mfma_f32_16x16x32_bf16 v[98:101], v[168:171], v[228:231], v[98:101]
	v_mfma_f32_16x16x32_bf16 v[102:105], v[122:125], v[228:231], v[102:105]
	v_mfma_f32_16x16x32_bf16 v[106:109], v[160:163], v[232:235], v[106:109]
	v_mfma_f32_16x16x32_bf16 v[110:113], v[164:167], v[232:235], v[110:113]
	v_mfma_f32_16x16x32_bf16 v[114:117], v[168:171], v[232:235], v[114:117]
	v_mfma_f32_16x16x32_bf16 v[118:121], v[122:125], v[232:235], v[118:121]
	v_mfma_f32_16x16x32_bf16 v[208:211], v[160:163], v[236:239], v[208:211]
	v_mfma_f32_16x16x32_bf16 v[212:215], v[164:167], v[236:239], v[212:215]
	v_mfma_f32_16x16x32_bf16 v[216:219], v[168:171], v[236:239], v[216:219]
	v_mfma_f32_16x16x32_bf16 v[220:223], v[122:125], v[236:239], v[220:223]
	s_mov_b32 s12, 9
